# EpiResid: lanes exchange half their accumulators (DPP row_ror:8) so each load/store instruction covers whole 128-byte lines
# speedup vs baseline: 1.0096x; 1.0086x over previous
;     __device__ __forceinline__ void operator()(const f32x4 (&acc)[2][2][4][2], const pg8::Unit& u, int wr, int wc, int fr, int fq) const {
;         const int row0 = u.pm * 256 + wr * 64 + fr; const float* gp = gate + (size_t)(u.pm >> 5) * NMOD;
; #pragma unroll
;         for (int bj = 0; bj < 2; ++bj) {
;             const int col = u.pn * 256 + bj * 128 + wc * 32 + 8 * fq;
;             const f32x4 g0 = *(const f32x4*)(gp + col) * coef, g1 = *(const f32x4*)(gp + col + 4) * coef;
; #pragma unroll
;             for (int ai = 0; ai < 2; ++ai)
; #pragma unroll
;                 for (int m = 0; m < 4; ++m) {
;                     const size_t off = (size_t)(row0 + ai * 128 + m * 16) * DM + col;
;                     const f32x4 x0 = *(const f32x4*)(base + off), x1 = *(const f32x4*)(base + off + 4);
;                     *(f32x4*)(out + off) = x0 + g0 * acc[ai][bj][m][0]; *(f32x4*)(out + off + 4) = x1 + g1 * acc[ai][bj][m][1];
;                     if (m & 1) asm volatile("" ::: "memory");
;                 }
;         }
;     }
.LBB0_235:
	v_and_b32_e32 v243, 8, v160
	v_sub_u32_e32 v240, v160, v243
	v_lshrrev_b32_e32 v243, 1, v243
	v_add_u32_e32 v241, v162, v243
	v_lshl_add_u32 v240, s70, 8, v240
	v_lshl_add_u32 v241, s71, 8, v241
	v_lshlrev_b32_e32 v240, 10, v240
	v_add_lshl_u32 v240, v240, v241, 2
	v_lshlrev_b32_e32 v241, 2, v241
	v_add_u32_e32 v242, 0x8000, v240
	s_ashr_i32 s98, s70, 5
	s_mul_i32 s98, s98, 0x9000
	s_add_u32 s98, s44, s98
	s_addc_u32 s99, s45, 0
	global_load_dwordx4 v[144:147], v241, s[98:99]
	s_add_u32 s100, s36, 0x0
	s_addc_u32 s101, s37, 0
	global_load_dwordx4 v[172:175], v240, s[100:101]
	global_load_dwordx4 v[176:179], v242, s[100:101]
	s_add_u32 s100, s36, 0x10000
	s_addc_u32 s101, s37, 0
	global_load_dwordx4 v[180:183], v240, s[100:101]
	global_load_dwordx4 v[184:187], v242, s[100:101]
	s_add_u32 s100, s36, 0x20000
	s_addc_u32 s101, s37, 0
	global_load_dwordx4 v[188:191], v240, s[100:101]
	global_load_dwordx4 v[192:195], v242, s[100:101]
	s_add_u32 s100, s36, 0x30000
	s_addc_u32 s101, s37, 0
	global_load_dwordx4 v[196:199], v240, s[100:101]
	global_load_dwordx4 v[200:203], v242, s[100:101]
	s_add_u32 s100, s36, 0x80000
	s_addc_u32 s101, s37, 0
	global_load_dwordx4 v[208:211], v240, s[100:101]
	global_load_dwordx4 v[212:215], v242, s[100:101]
	s_add_u32 s100, s36, 0x90000
	s_addc_u32 s101, s37, 0
	global_load_dwordx4 v[216:219], v240, s[100:101]
	global_load_dwordx4 v[220:223], v242, s[100:101]
	s_add_u32 s100, s36, 0xa0000
	s_addc_u32 s101, s37, 0
	global_load_dwordx4 v[224:227], v240, s[100:101]
	global_load_dwordx4 v[228:231], v242, s[100:101]
	s_add_u32 s100, s36, 0xb0000
	s_addc_u32 s101, s37, 0
	global_load_dwordx4 v[232:235], v240, s[100:101]
	global_load_dwordx4 v[236:239], v242, s[100:101]
	v_mov_b32_dpp v148, v120 row_ror:8 row_mask:0xf bank_mask:0xf
	v_mov_b32_dpp v149, v121 row_ror:8 row_mask:0xf bank_mask:0xf
	v_mov_b32_dpp v150, v122 row_ror:8 row_mask:0xf bank_mask:0xf
	v_mov_b32_dpp v151, v123 row_ror:8 row_mask:0xf bank_mask:0xf
	v_mov_b32_dpp v120, v124 row_ror:8 row_mask:0xf bank_mask:0x3
	v_mov_b32_dpp v121, v125 row_ror:8 row_mask:0xf bank_mask:0x3
	v_mov_b32_dpp v122, v126 row_ror:8 row_mask:0xf bank_mask:0x3
	v_mov_b32_dpp v123, v127 row_ror:8 row_mask:0xf bank_mask:0x3
	v_mov_b32_dpp v124, v148 quad_perm:[0,1,2,3] row_mask:0xf bank_mask:0xc
	v_mov_b32_dpp v125, v149 quad_perm:[0,1,2,3] row_mask:0xf bank_mask:0xc
	v_mov_b32_dpp v126, v150 quad_perm:[0,1,2,3] row_mask:0xf bank_mask:0xc
	v_mov_b32_dpp v127, v151 quad_perm:[0,1,2,3] row_mask:0xf bank_mask:0xc
	s_waitcnt vmcnt(16)
	v_pk_mul_f32 v[144:145], v[144:145], 0.5 op_sel_hi:[1,0]
	v_pk_mul_f32 v[146:147], v[146:147], 0.5 op_sel_hi:[1,0]
	s_waitcnt vmcnt(14)
	v_pk_fma_f32 v[124:125], v[124:125], v[144:145], v[172:173]
	v_pk_fma_f32 v[126:127], v[126:127], v[146:147], v[174:175]
	v_pk_fma_f32 v[120:121], v[120:121], v[144:145], v[176:177]
	v_pk_fma_f32 v[122:123], v[122:123], v[146:147], v[178:179]
	s_add_u32 s98, s90, 0x0
	s_addc_u32 s99, s91, 0
	global_store_dwordx4 v240, v[124:127], s[98:99]
	global_store_dwordx4 v242, v[120:123], s[98:99]
	s_add_u32 s100, s36, 0x0
	s_addc_u32 s101, s37, 0
	global_load_dwordx4 v[172:175], v240, s[100:101] offset:512
	global_load_dwordx4 v[176:179], v242, s[100:101] offset:512
	s_ashr_i32 s98, s70, 5
	s_mul_i32 s98, s98, 0x9000
	s_add_u32 s98, s44, s98
	s_addc_u32 s99, s45, 0
	global_load_dwordx4 v[120:123], v241, s[98:99] offset:512
	v_mov_b32_dpp v148, v112 row_ror:8 row_mask:0xf bank_mask:0xf
	v_mov_b32_dpp v149, v113 row_ror:8 row_mask:0xf bank_mask:0xf
	v_mov_b32_dpp v150, v114 row_ror:8 row_mask:0xf bank_mask:0xf
	v_mov_b32_dpp v151, v115 row_ror:8 row_mask:0xf bank_mask:0xf
	v_mov_b32_dpp v112, v116 row_ror:8 row_mask:0xf bank_mask:0x3
	v_mov_b32_dpp v113, v117 row_ror:8 row_mask:0xf bank_mask:0x3
	v_mov_b32_dpp v114, v118 row_ror:8 row_mask:0xf bank_mask:0x3
	v_mov_b32_dpp v115, v119 row_ror:8 row_mask:0xf bank_mask:0x3
	v_mov_b32_dpp v116, v148 quad_perm:[0,1,2,3] row_mask:0xf bank_mask:0xc
	v_mov_b32_dpp v117, v149 quad_perm:[0,1,2,3] row_mask:0xf bank_mask:0xc
	v_mov_b32_dpp v118, v150 quad_perm:[0,1,2,3] row_mask:0xf bank_mask:0xc
	v_mov_b32_dpp v119, v151 quad_perm:[0,1,2,3] row_mask:0xf bank_mask:0xc
	s_waitcnt vmcnt(17)
	v_pk_fma_f32 v[116:117], v[116:117], v[144:145], v[180:181]
	v_pk_fma_f32 v[118:119], v[118:119], v[146:147], v[182:183]
	v_pk_fma_f32 v[112:113], v[112:113], v[144:145], v[184:185]
	v_pk_fma_f32 v[114:115], v[114:115], v[146:147], v[186:187]
	s_add_u32 s98, s90, 0x10000
	s_addc_u32 s99, s91, 0
	global_store_dwordx4 v240, v[116:119], s[98:99]
	global_store_dwordx4 v242, v[112:115], s[98:99]
	s_add_u32 s100, s36, 0x10000
	s_addc_u32 s101, s37, 0
	global_load_dwordx4 v[180:183], v240, s[100:101] offset:512
	global_load_dwordx4 v[184:187], v242, s[100:101] offset:512
	v_mov_b32_dpp v148, v104 row_ror:8 row_mask:0xf bank_mask:0xf
	v_mov_b32_dpp v149, v105 row_ror:8 row_mask:0xf bank_mask:0xf
	v_mov_b32_dpp v150, v106 row_ror:8 row_mask:0xf bank_mask:0xf
	v_mov_b32_dpp v151, v107 row_ror:8 row_mask:0xf bank_mask:0xf
	v_mov_b32_dpp v104, v108 row_ror:8 row_mask:0xf bank_mask:0x3
	v_mov_b32_dpp v105, v109 row_ror:8 row_mask:0xf bank_mask:0x3
	v_mov_b32_dpp v106, v110 row_ror:8 row_mask:0xf bank_mask:0x3
	v_mov_b32_dpp v107, v111 row_ror:8 row_mask:0xf bank_mask:0x3
	v_mov_b32_dpp v108, v148 quad_perm:[0,1,2,3] row_mask:0xf bank_mask:0xc
	v_mov_b32_dpp v109, v149 quad_perm:[0,1,2,3] row_mask:0xf bank_mask:0xc
	v_mov_b32_dpp v110, v150 quad_perm:[0,1,2,3] row_mask:0xf bank_mask:0xc
	v_mov_b32_dpp v111, v151 quad_perm:[0,1,2,3] row_mask:0xf bank_mask:0xc
	s_waitcnt vmcnt(19)
;     __device__ __forceinline__ void operator()(const f32x4 (&acc)[2][2][4][2], const pg8::Unit& u, int wr, int wc, int fr, int fq) const {
;         const int row0 = u.pm * 256 + wr * 64 + fr; const float* gp = gate + (size_t)(u.pm >> 5) * NMOD;
; #pragma unroll
;         for (int bj = 0; bj < 2; ++bj) {
;             const int col = u.pn * 256 + bj * 128 + wc * 32 + 8 * fq;
;             const f32x4 g0 = *(const f32x4*)(gp + col) * coef, g1 = *(const f32x4*)(gp + col + 4) * coef;
; #pragma unroll
;             for (int ai = 0; ai < 2; ++ai)
; #pragma unroll
;                 for (int m = 0; m < 4; ++m) {
;                     const size_t off = (size_t)(row0 + ai * 128 + m * 16) * DM + col;
;                     const f32x4 x0 = *(const f32x4*)(base + off), x1 = *(const f32x4*)(base + off + 4);
;                     *(f32x4*)(out + off) = x0 + g0 * acc[ai][bj][m][0]; *(f32x4*)(out + off + 4) = x1 + g1 * acc[ai][bj][m][1];
;                     if (m & 1) asm volatile("" ::: "memory");
;                 }
;         }
;     }
	v_pk_fma_f32 v[108:109], v[108:109], v[144:145], v[188:189]
	v_pk_fma_f32 v[110:111], v[110:111], v[146:147], v[190:191]
	v_pk_fma_f32 v[104:105], v[104:105], v[144:145], v[192:193]
	v_pk_fma_f32 v[106:107], v[106:107], v[146:147], v[194:195]
	s_add_u32 s98, s90, 0x20000
	s_addc_u32 s99, s91, 0
	global_store_dwordx4 v240, v[108:111], s[98:99]
	global_store_dwordx4 v242, v[104:107], s[98:99]
	s_add_u32 s100, s36, 0x20000
	s_addc_u32 s101, s37, 0
	global_load_dwordx4 v[188:191], v240, s[100:101] offset:512
	global_load_dwordx4 v[192:195], v242, s[100:101] offset:512
	v_mov_b32_dpp v148, v96 row_ror:8 row_mask:0xf bank_mask:0xf
	v_mov_b32_dpp v149, v97 row_ror:8 row_mask:0xf bank_mask:0xf
	v_mov_b32_dpp v150, v98 row_ror:8 row_mask:0xf bank_mask:0xf
	v_mov_b32_dpp v151, v99 row_ror:8 row_mask:0xf bank_mask:0xf
	v_mov_b32_dpp v96, v100 row_ror:8 row_mask:0xf bank_mask:0x3
	v_mov_b32_dpp v97, v101 row_ror:8 row_mask:0xf bank_mask:0x3
	v_mov_b32_dpp v98, v102 row_ror:8 row_mask:0xf bank_mask:0x3
	v_mov_b32_dpp v99, v103 row_ror:8 row_mask:0xf bank_mask:0x3
	v_mov_b32_dpp v100, v148 quad_perm:[0,1,2,3] row_mask:0xf bank_mask:0xc
	v_mov_b32_dpp v101, v149 quad_perm:[0,1,2,3] row_mask:0xf bank_mask:0xc
	v_mov_b32_dpp v102, v150 quad_perm:[0,1,2,3] row_mask:0xf bank_mask:0xc
	v_mov_b32_dpp v103, v151 quad_perm:[0,1,2,3] row_mask:0xf bank_mask:0xc
	s_waitcnt vmcnt(21)
	v_pk_fma_f32 v[100:101], v[100:101], v[144:145], v[196:197]
	v_pk_fma_f32 v[102:103], v[102:103], v[146:147], v[198:199]
	v_pk_fma_f32 v[96:97], v[96:97], v[144:145], v[200:201]
	v_pk_fma_f32 v[98:99], v[98:99], v[146:147], v[202:203]
	s_add_u32 s98, s90, 0x30000
	s_addc_u32 s99, s91, 0
	global_store_dwordx4 v240, v[100:103], s[98:99]
	global_store_dwordx4 v242, v[96:99], s[98:99]
	s_add_u32 s100, s36, 0x30000
	s_addc_u32 s101, s37, 0
	global_load_dwordx4 v[196:199], v240, s[100:101] offset:512
	global_load_dwordx4 v[200:203], v242, s[100:101] offset:512
	v_mov_b32_dpp v148, v88 row_ror:8 row_mask:0xf bank_mask:0xf
	v_mov_b32_dpp v149, v89 row_ror:8 row_mask:0xf bank_mask:0xf
	v_mov_b32_dpp v150, v90 row_ror:8 row_mask:0xf bank_mask:0xf
	v_mov_b32_dpp v151, v91 row_ror:8 row_mask:0xf bank_mask:0xf
	v_mov_b32_dpp v88, v92 row_ror:8 row_mask:0xf bank_mask:0x3
	v_mov_b32_dpp v89, v93 row_ror:8 row_mask:0xf bank_mask:0x3
	v_mov_b32_dpp v90, v94 row_ror:8 row_mask:0xf bank_mask:0x3
	v_mov_b32_dpp v91, v95 row_ror:8 row_mask:0xf bank_mask:0x3
	v_mov_b32_dpp v92, v148 quad_perm:[0,1,2,3] row_mask:0xf bank_mask:0xc
	v_mov_b32_dpp v93, v149 quad_perm:[0,1,2,3] row_mask:0xf bank_mask:0xc
	v_mov_b32_dpp v94, v150 quad_perm:[0,1,2,3] row_mask:0xf bank_mask:0xc
	v_mov_b32_dpp v95, v151 quad_perm:[0,1,2,3] row_mask:0xf bank_mask:0xc
	s_waitcnt vmcnt(23)
	v_pk_fma_f32 v[92:93], v[92:93], v[144:145], v[208:209]
	v_pk_fma_f32 v[94:95], v[94:95], v[146:147], v[210:211]
	v_pk_fma_f32 v[88:89], v[88:89], v[144:145], v[212:213]
	v_pk_fma_f32 v[90:91], v[90:91], v[146:147], v[214:215]
	s_add_u32 s98, s90, 0x80000
	s_addc_u32 s99, s91, 0
	global_store_dwordx4 v240, v[92:95], s[98:99]
	global_store_dwordx4 v242, v[88:91], s[98:99]
	s_add_u32 s100, s36, 0x80000
	s_addc_u32 s101, s37, 0
	global_load_dwordx4 v[208:211], v240, s[100:101] offset:512
	global_load_dwordx4 v[212:215], v242, s[100:101] offset:512
	v_mov_b32_dpp v148, v80 row_ror:8 row_mask:0xf bank_mask:0xf
	v_mov_b32_dpp v149, v81 row_ror:8 row_mask:0xf bank_mask:0xf
	v_mov_b32_dpp v150, v82 row_ror:8 row_mask:0xf bank_mask:0xf
	v_mov_b32_dpp v151, v83 row_ror:8 row_mask:0xf bank_mask:0xf
	v_mov_b32_dpp v80, v84 row_ror:8 row_mask:0xf bank_mask:0x3
	v_mov_b32_dpp v81, v85 row_ror:8 row_mask:0xf bank_mask:0x3
	v_mov_b32_dpp v82, v86 row_ror:8 row_mask:0xf bank_mask:0x3
	v_mov_b32_dpp v83, v87 row_ror:8 row_mask:0xf bank_mask:0x3
	v_mov_b32_dpp v84, v148 quad_perm:[0,1,2,3] row_mask:0xf bank_mask:0xc
	v_mov_b32_dpp v85, v149 quad_perm:[0,1,2,3] row_mask:0xf bank_mask:0xc
	v_mov_b32_dpp v86, v150 quad_perm:[0,1,2,3] row_mask:0xf bank_mask:0xc
	v_mov_b32_dpp v87, v151 quad_perm:[0,1,2,3] row_mask:0xf bank_mask:0xc
	s_waitcnt vmcnt(25)
	v_pk_fma_f32 v[84:85], v[84:85], v[144:145], v[216:217]
	v_pk_fma_f32 v[86:87], v[86:87], v[146:147], v[218:219]
	v_pk_fma_f32 v[80:81], v[80:81], v[144:145], v[220:221]
	v_pk_fma_f32 v[82:83], v[82:83], v[146:147], v[222:223]
	s_add_u32 s98, s90, 0x90000
	s_addc_u32 s99, s91, 0
	global_store_dwordx4 v240, v[84:87], s[98:99]
	global_store_dwordx4 v242, v[80:83], s[98:99]
	s_add_u32 s100, s36, 0x90000
	s_addc_u32 s101, s37, 0
	global_load_dwordx4 v[216:219], v240, s[100:101] offset:512
	global_load_dwordx4 v[220:223], v242, s[100:101] offset:512
	v_mov_b32_dpp v148, v72 row_ror:8 row_mask:0xf bank_mask:0xf
	v_mov_b32_dpp v149, v73 row_ror:8 row_mask:0xf bank_mask:0xf
	v_mov_b32_dpp v150, v74 row_ror:8 row_mask:0xf bank_mask:0xf
	v_mov_b32_dpp v151, v75 row_ror:8 row_mask:0xf bank_mask:0xf
	v_mov_b32_dpp v72, v76 row_ror:8 row_mask:0xf bank_mask:0x3
	v_mov_b32_dpp v73, v77 row_ror:8 row_mask:0xf bank_mask:0x3
	v_mov_b32_dpp v74, v78 row_ror:8 row_mask:0xf bank_mask:0x3
	v_mov_b32_dpp v75, v79 row_ror:8 row_mask:0xf bank_mask:0x3
	v_mov_b32_dpp v76, v148 quad_perm:[0,1,2,3] row_mask:0xf bank_mask:0xc
	v_mov_b32_dpp v77, v149 quad_perm:[0,1,2,3] row_mask:0xf bank_mask:0xc
	v_mov_b32_dpp v78, v150 quad_perm:[0,1,2,3] row_mask:0xf bank_mask:0xc
	v_mov_b32_dpp v79, v151 quad_perm:[0,1,2,3] row_mask:0xf bank_mask:0xc
	s_waitcnt vmcnt(27)
;     __device__ __forceinline__ void operator()(const f32x4 (&acc)[2][2][4][2], const pg8::Unit& u, int wr, int wc, int fr, int fq) const {
;         const int row0 = u.pm * 256 + wr * 64 + fr; const float* gp = gate + (size_t)(u.pm >> 5) * NMOD;
; #pragma unroll
;         for (int bj = 0; bj < 2; ++bj) {
;             const int col = u.pn * 256 + bj * 128 + wc * 32 + 8 * fq;
;             const f32x4 g0 = *(const f32x4*)(gp + col) * coef, g1 = *(const f32x4*)(gp + col + 4) * coef;
; #pragma unroll
;             for (int ai = 0; ai < 2; ++ai)
; #pragma unroll
;                 for (int m = 0; m < 4; ++m) {
;                     const size_t off = (size_t)(row0 + ai * 128 + m * 16) * DM + col;
;                     const f32x4 x0 = *(const f32x4*)(base + off), x1 = *(const f32x4*)(base + off + 4);
;                     *(f32x4*)(out + off) = x0 + g0 * acc[ai][bj][m][0]; *(f32x4*)(out + off + 4) = x1 + g1 * acc[ai][bj][m][1];
;                     if (m & 1) asm volatile("" ::: "memory");
;                 }
;         }
;     }
	v_pk_fma_f32 v[76:77], v[76:77], v[144:145], v[224:225]
	v_pk_fma_f32 v[78:79], v[78:79], v[146:147], v[226:227]
	v_pk_fma_f32 v[72:73], v[72:73], v[144:145], v[228:229]
	v_pk_fma_f32 v[74:75], v[74:75], v[146:147], v[230:231]
	s_add_u32 s98, s90, 0xa0000
	s_addc_u32 s99, s91, 0
	global_store_dwordx4 v240, v[76:79], s[98:99]
	global_store_dwordx4 v242, v[72:75], s[98:99]
	s_add_u32 s100, s36, 0xa0000
	s_addc_u32 s101, s37, 0
	global_load_dwordx4 v[224:227], v240, s[100:101] offset:512
	global_load_dwordx4 v[228:231], v242, s[100:101] offset:512
	v_mov_b32_dpp v148, v64 row_ror:8 row_mask:0xf bank_mask:0xf
	v_mov_b32_dpp v149, v65 row_ror:8 row_mask:0xf bank_mask:0xf
	v_mov_b32_dpp v150, v66 row_ror:8 row_mask:0xf bank_mask:0xf
	v_mov_b32_dpp v151, v67 row_ror:8 row_mask:0xf bank_mask:0xf
	v_mov_b32_dpp v64, v68 row_ror:8 row_mask:0xf bank_mask:0x3
	v_mov_b32_dpp v65, v69 row_ror:8 row_mask:0xf bank_mask:0x3
	v_mov_b32_dpp v66, v70 row_ror:8 row_mask:0xf bank_mask:0x3
	v_mov_b32_dpp v67, v71 row_ror:8 row_mask:0xf bank_mask:0x3
	v_mov_b32_dpp v68, v148 quad_perm:[0,1,2,3] row_mask:0xf bank_mask:0xc
	v_mov_b32_dpp v69, v149 quad_perm:[0,1,2,3] row_mask:0xf bank_mask:0xc
	v_mov_b32_dpp v70, v150 quad_perm:[0,1,2,3] row_mask:0xf bank_mask:0xc
	v_mov_b32_dpp v71, v151 quad_perm:[0,1,2,3] row_mask:0xf bank_mask:0xc
	s_waitcnt vmcnt(29)
	v_pk_fma_f32 v[68:69], v[68:69], v[144:145], v[232:233]
	v_pk_fma_f32 v[70:71], v[70:71], v[146:147], v[234:235]
	v_pk_fma_f32 v[64:65], v[64:65], v[144:145], v[236:237]
	v_pk_fma_f32 v[66:67], v[66:67], v[146:147], v[238:239]
	s_add_u32 s98, s90, 0xb0000
	s_addc_u32 s99, s91, 0
	global_store_dwordx4 v240, v[68:71], s[98:99]
	global_store_dwordx4 v242, v[64:67], s[98:99]
	s_add_u32 s100, s36, 0xb0000
	s_addc_u32 s101, s37, 0
	global_load_dwordx4 v[232:235], v240, s[100:101] offset:512
	global_load_dwordx4 v[236:239], v242, s[100:101] offset:512
	v_mov_b32_dpp v148, v56 row_ror:8 row_mask:0xf bank_mask:0xf
	v_mov_b32_dpp v149, v57 row_ror:8 row_mask:0xf bank_mask:0xf
	v_mov_b32_dpp v150, v58 row_ror:8 row_mask:0xf bank_mask:0xf
	v_mov_b32_dpp v151, v59 row_ror:8 row_mask:0xf bank_mask:0xf
	v_mov_b32_dpp v56, v60 row_ror:8 row_mask:0xf bank_mask:0x3
	v_mov_b32_dpp v57, v61 row_ror:8 row_mask:0xf bank_mask:0x3
	v_mov_b32_dpp v58, v62 row_ror:8 row_mask:0xf bank_mask:0x3
	v_mov_b32_dpp v59, v63 row_ror:8 row_mask:0xf bank_mask:0x3
	v_mov_b32_dpp v60, v148 quad_perm:[0,1,2,3] row_mask:0xf bank_mask:0xc
	v_mov_b32_dpp v61, v149 quad_perm:[0,1,2,3] row_mask:0xf bank_mask:0xc
	v_mov_b32_dpp v62, v150 quad_perm:[0,1,2,3] row_mask:0xf bank_mask:0xc
	v_mov_b32_dpp v63, v151 quad_perm:[0,1,2,3] row_mask:0xf bank_mask:0xc
	s_waitcnt vmcnt(28)
	v_pk_mul_f32 v[120:121], v[120:121], 0.5 op_sel_hi:[1,0]
	v_pk_mul_f32 v[122:123], v[122:123], 0.5 op_sel_hi:[1,0]
	v_pk_fma_f32 v[60:61], v[60:61], v[120:121], v[172:173]
	v_pk_fma_f32 v[62:63], v[62:63], v[122:123], v[174:175]
	v_pk_fma_f32 v[56:57], v[56:57], v[120:121], v[176:177]
	v_pk_fma_f32 v[58:59], v[58:59], v[122:123], v[178:179]
	s_add_u32 s98, s90, 0x0
	s_addc_u32 s99, s91, 0
	global_store_dwordx4 v240, v[60:63], s[98:99] offset:512
	global_store_dwordx4 v242, v[56:59], s[98:99] offset:512
	v_mov_b32_dpp v148, v48 row_ror:8 row_mask:0xf bank_mask:0xf
	v_mov_b32_dpp v149, v49 row_ror:8 row_mask:0xf bank_mask:0xf
	v_mov_b32_dpp v150, v50 row_ror:8 row_mask:0xf bank_mask:0xf
	v_mov_b32_dpp v151, v51 row_ror:8 row_mask:0xf bank_mask:0xf
	v_mov_b32_dpp v48, v52 row_ror:8 row_mask:0xf bank_mask:0x3
	v_mov_b32_dpp v49, v53 row_ror:8 row_mask:0xf bank_mask:0x3
	v_mov_b32_dpp v50, v54 row_ror:8 row_mask:0xf bank_mask:0x3
	v_mov_b32_dpp v51, v55 row_ror:8 row_mask:0xf bank_mask:0x3
	v_mov_b32_dpp v52, v148 quad_perm:[0,1,2,3] row_mask:0xf bank_mask:0xc
	v_mov_b32_dpp v53, v149 quad_perm:[0,1,2,3] row_mask:0xf bank_mask:0xc
	v_mov_b32_dpp v54, v150 quad_perm:[0,1,2,3] row_mask:0xf bank_mask:0xc
	v_mov_b32_dpp v55, v151 quad_perm:[0,1,2,3] row_mask:0xf bank_mask:0xc
	s_waitcnt vmcnt(26)
	v_pk_fma_f32 v[52:53], v[52:53], v[120:121], v[180:181]
	v_pk_fma_f32 v[54:55], v[54:55], v[122:123], v[182:183]
	v_pk_fma_f32 v[48:49], v[48:49], v[120:121], v[184:185]
	v_pk_fma_f32 v[50:51], v[50:51], v[122:123], v[186:187]
	s_add_u32 s98, s90, 0x10000
	s_addc_u32 s99, s91, 0
	global_store_dwordx4 v240, v[52:55], s[98:99] offset:512
	global_store_dwordx4 v242, v[48:51], s[98:99] offset:512
	v_mov_b32_dpp v148, v40 row_ror:8 row_mask:0xf bank_mask:0xf
	v_mov_b32_dpp v149, v41 row_ror:8 row_mask:0xf bank_mask:0xf
	v_mov_b32_dpp v150, v42 row_ror:8 row_mask:0xf bank_mask:0xf
	v_mov_b32_dpp v151, v43 row_ror:8 row_mask:0xf bank_mask:0xf
	v_mov_b32_dpp v40, v44 row_ror:8 row_mask:0xf bank_mask:0x3
	v_mov_b32_dpp v41, v45 row_ror:8 row_mask:0xf bank_mask:0x3
	v_mov_b32_dpp v42, v46 row_ror:8 row_mask:0xf bank_mask:0x3
	v_mov_b32_dpp v43, v47 row_ror:8 row_mask:0xf bank_mask:0x3
	v_mov_b32_dpp v44, v148 quad_perm:[0,1,2,3] row_mask:0xf bank_mask:0xc
	v_mov_b32_dpp v45, v149 quad_perm:[0,1,2,3] row_mask:0xf bank_mask:0xc
	v_mov_b32_dpp v46, v150 quad_perm:[0,1,2,3] row_mask:0xf bank_mask:0xc
	v_mov_b32_dpp v47, v151 quad_perm:[0,1,2,3] row_mask:0xf bank_mask:0xc
	s_waitcnt vmcnt(24)
;     __device__ __forceinline__ void operator()(const f32x4 (&acc)[2][2][4][2], const pg8::Unit& u, int wr, int wc, int fr, int fq) const {
;         const int row0 = u.pm * 256 + wr * 64 + fr; const float* gp = gate + (size_t)(u.pm >> 5) * NMOD;
; #pragma unroll
;         for (int bj = 0; bj < 2; ++bj) {
;             const int col = u.pn * 256 + bj * 128 + wc * 32 + 8 * fq;
;             const f32x4 g0 = *(const f32x4*)(gp + col) * coef, g1 = *(const f32x4*)(gp + col + 4) * coef;
; #pragma unroll
;             for (int ai = 0; ai < 2; ++ai)
; #pragma unroll
;                 for (int m = 0; m < 4; ++m) {
;                     const size_t off = (size_t)(row0 + ai * 128 + m * 16) * DM + col;
;                     const f32x4 x0 = *(const f32x4*)(base + off), x1 = *(const f32x4*)(base + off + 4);
;                     *(f32x4*)(out + off) = x0 + g0 * acc[ai][bj][m][0]; *(f32x4*)(out + off + 4) = x1 + g1 * acc[ai][bj][m][1];
;                     if (m & 1) asm volatile("" ::: "memory");
;                 }
;         }
;     }
	v_pk_fma_f32 v[44:45], v[44:45], v[120:121], v[188:189]
	v_pk_fma_f32 v[46:47], v[46:47], v[122:123], v[190:191]
	v_pk_fma_f32 v[40:41], v[40:41], v[120:121], v[192:193]
	v_pk_fma_f32 v[42:43], v[42:43], v[122:123], v[194:195]
	s_add_u32 s98, s90, 0x20000
	s_addc_u32 s99, s91, 0
	global_store_dwordx4 v240, v[44:47], s[98:99] offset:512
	global_store_dwordx4 v242, v[40:43], s[98:99] offset:512
	v_mov_b32_dpp v148, v32 row_ror:8 row_mask:0xf bank_mask:0xf
	v_mov_b32_dpp v149, v33 row_ror:8 row_mask:0xf bank_mask:0xf
	v_mov_b32_dpp v150, v34 row_ror:8 row_mask:0xf bank_mask:0xf
	v_mov_b32_dpp v151, v35 row_ror:8 row_mask:0xf bank_mask:0xf
	v_mov_b32_dpp v32, v36 row_ror:8 row_mask:0xf bank_mask:0x3
	v_mov_b32_dpp v33, v37 row_ror:8 row_mask:0xf bank_mask:0x3
	v_mov_b32_dpp v34, v38 row_ror:8 row_mask:0xf bank_mask:0x3
	v_mov_b32_dpp v35, v39 row_ror:8 row_mask:0xf bank_mask:0x3
	v_mov_b32_dpp v36, v148 quad_perm:[0,1,2,3] row_mask:0xf bank_mask:0xc
	v_mov_b32_dpp v37, v149 quad_perm:[0,1,2,3] row_mask:0xf bank_mask:0xc
	v_mov_b32_dpp v38, v150 quad_perm:[0,1,2,3] row_mask:0xf bank_mask:0xc
	v_mov_b32_dpp v39, v151 quad_perm:[0,1,2,3] row_mask:0xf bank_mask:0xc
	s_waitcnt vmcnt(22)
	v_pk_fma_f32 v[36:37], v[36:37], v[120:121], v[196:197]
	v_pk_fma_f32 v[38:39], v[38:39], v[122:123], v[198:199]
	v_pk_fma_f32 v[32:33], v[32:33], v[120:121], v[200:201]
	v_pk_fma_f32 v[34:35], v[34:35], v[122:123], v[202:203]
	s_add_u32 s98, s90, 0x30000
	s_addc_u32 s99, s91, 0
	global_store_dwordx4 v240, v[36:39], s[98:99] offset:512
	global_store_dwordx4 v242, v[32:35], s[98:99] offset:512
	v_mov_b32_dpp v148, v24 row_ror:8 row_mask:0xf bank_mask:0xf
	v_mov_b32_dpp v149, v25 row_ror:8 row_mask:0xf bank_mask:0xf
	v_mov_b32_dpp v150, v26 row_ror:8 row_mask:0xf bank_mask:0xf
	v_mov_b32_dpp v151, v27 row_ror:8 row_mask:0xf bank_mask:0xf
	v_mov_b32_dpp v24, v28 row_ror:8 row_mask:0xf bank_mask:0x3
	v_mov_b32_dpp v25, v29 row_ror:8 row_mask:0xf bank_mask:0x3
	v_mov_b32_dpp v26, v30 row_ror:8 row_mask:0xf bank_mask:0x3
	v_mov_b32_dpp v27, v31 row_ror:8 row_mask:0xf bank_mask:0x3
	v_mov_b32_dpp v28, v148 quad_perm:[0,1,2,3] row_mask:0xf bank_mask:0xc
	v_mov_b32_dpp v29, v149 quad_perm:[0,1,2,3] row_mask:0xf bank_mask:0xc
	v_mov_b32_dpp v30, v150 quad_perm:[0,1,2,3] row_mask:0xf bank_mask:0xc
	v_mov_b32_dpp v31, v151 quad_perm:[0,1,2,3] row_mask:0xf bank_mask:0xc
	s_waitcnt vmcnt(20)
	v_pk_fma_f32 v[28:29], v[28:29], v[120:121], v[208:209]
	v_pk_fma_f32 v[30:31], v[30:31], v[122:123], v[210:211]
	v_pk_fma_f32 v[24:25], v[24:25], v[120:121], v[212:213]
	v_pk_fma_f32 v[26:27], v[26:27], v[122:123], v[214:215]
	s_add_u32 s98, s90, 0x80000
	s_addc_u32 s99, s91, 0
	global_store_dwordx4 v240, v[28:31], s[98:99] offset:512
	global_store_dwordx4 v242, v[24:27], s[98:99] offset:512
	v_mov_b32_dpp v148, v16 row_ror:8 row_mask:0xf bank_mask:0xf
	v_mov_b32_dpp v149, v17 row_ror:8 row_mask:0xf bank_mask:0xf
	v_mov_b32_dpp v150, v18 row_ror:8 row_mask:0xf bank_mask:0xf
	v_mov_b32_dpp v151, v19 row_ror:8 row_mask:0xf bank_mask:0xf
	v_mov_b32_dpp v16, v20 row_ror:8 row_mask:0xf bank_mask:0x3
	v_mov_b32_dpp v17, v21 row_ror:8 row_mask:0xf bank_mask:0x3
	v_mov_b32_dpp v18, v22 row_ror:8 row_mask:0xf bank_mask:0x3
	v_mov_b32_dpp v19, v23 row_ror:8 row_mask:0xf bank_mask:0x3
	v_mov_b32_dpp v20, v148 quad_perm:[0,1,2,3] row_mask:0xf bank_mask:0xc
	v_mov_b32_dpp v21, v149 quad_perm:[0,1,2,3] row_mask:0xf bank_mask:0xc
	v_mov_b32_dpp v22, v150 quad_perm:[0,1,2,3] row_mask:0xf bank_mask:0xc
	v_mov_b32_dpp v23, v151 quad_perm:[0,1,2,3] row_mask:0xf bank_mask:0xc
	s_waitcnt vmcnt(18)
	v_pk_fma_f32 v[20:21], v[20:21], v[120:121], v[216:217]
	v_pk_fma_f32 v[22:23], v[22:23], v[122:123], v[218:219]
	v_pk_fma_f32 v[16:17], v[16:17], v[120:121], v[220:221]
	v_pk_fma_f32 v[18:19], v[18:19], v[122:123], v[222:223]
	s_add_u32 s98, s90, 0x90000
	s_addc_u32 s99, s91, 0
	global_store_dwordx4 v240, v[20:23], s[98:99] offset:512
	global_store_dwordx4 v242, v[16:19], s[98:99] offset:512
	v_mov_b32_dpp v148, v8 row_ror:8 row_mask:0xf bank_mask:0xf
	v_mov_b32_dpp v149, v9 row_ror:8 row_mask:0xf bank_mask:0xf
	v_mov_b32_dpp v150, v10 row_ror:8 row_mask:0xf bank_mask:0xf
	v_mov_b32_dpp v151, v11 row_ror:8 row_mask:0xf bank_mask:0xf
	v_mov_b32_dpp v8, v12 row_ror:8 row_mask:0xf bank_mask:0x3
	v_mov_b32_dpp v9, v13 row_ror:8 row_mask:0xf bank_mask:0x3
	v_mov_b32_dpp v10, v14 row_ror:8 row_mask:0xf bank_mask:0x3
	v_mov_b32_dpp v11, v15 row_ror:8 row_mask:0xf bank_mask:0x3
	v_mov_b32_dpp v12, v148 quad_perm:[0,1,2,3] row_mask:0xf bank_mask:0xc
	v_mov_b32_dpp v13, v149 quad_perm:[0,1,2,3] row_mask:0xf bank_mask:0xc
	v_mov_b32_dpp v14, v150 quad_perm:[0,1,2,3] row_mask:0xf bank_mask:0xc
	v_mov_b32_dpp v15, v151 quad_perm:[0,1,2,3] row_mask:0xf bank_mask:0xc
	s_waitcnt vmcnt(16)
	v_pk_fma_f32 v[12:13], v[12:13], v[120:121], v[224:225]
	v_pk_fma_f32 v[14:15], v[14:15], v[122:123], v[226:227]
	v_pk_fma_f32 v[8:9], v[8:9], v[120:121], v[228:229]
	v_pk_fma_f32 v[10:11], v[10:11], v[122:123], v[230:231]
	s_add_u32 s98, s90, 0xa0000
	s_addc_u32 s99, s91, 0
	global_store_dwordx4 v240, v[12:15], s[98:99] offset:512
	global_store_dwordx4 v242, v[8:11], s[98:99] offset:512
	v_mov_b32_dpp v148, v0 row_ror:8 row_mask:0xf bank_mask:0xf
	v_mov_b32_dpp v149, v1 row_ror:8 row_mask:0xf bank_mask:0xf
	v_mov_b32_dpp v150, v2 row_ror:8 row_mask:0xf bank_mask:0xf
	v_mov_b32_dpp v151, v3 row_ror:8 row_mask:0xf bank_mask:0xf
	v_mov_b32_dpp v0, v4 row_ror:8 row_mask:0xf bank_mask:0x3
	v_mov_b32_dpp v1, v5 row_ror:8 row_mask:0xf bank_mask:0x3
	v_mov_b32_dpp v2, v6 row_ror:8 row_mask:0xf bank_mask:0x3
	v_mov_b32_dpp v3, v7 row_ror:8 row_mask:0xf bank_mask:0x3
	v_mov_b32_dpp v4, v148 quad_perm:[0,1,2,3] row_mask:0xf bank_mask:0xc
	v_mov_b32_dpp v5, v149 quad_perm:[0,1,2,3] row_mask:0xf bank_mask:0xc
	v_mov_b32_dpp v6, v150 quad_perm:[0,1,2,3] row_mask:0xf bank_mask:0xc
	v_mov_b32_dpp v7, v151 quad_perm:[0,1,2,3] row_mask:0xf bank_mask:0xc
	s_waitcnt vmcnt(14)
	v_pk_fma_f32 v[4:5], v[4:5], v[120:121], v[232:233]
	v_pk_fma_f32 v[6:7], v[6:7], v[122:123], v[234:235]
	v_pk_fma_f32 v[0:1], v[0:1], v[120:121], v[236:237]
	v_pk_fma_f32 v[2:3], v[2:3], v[122:123], v[238:239]
	s_add_u32 s98, s90, 0xb0000
	s_addc_u32 s99, s91, 0
	global_store_dwordx4 v240, v[4:7], s[98:99] offset:512
	global_store_dwordx4 v242, v[0:3], s[98:99] offset:512
	s_and_b64 vcc, exec, s[6:7]
	s_mov_b64 s[24:25], -1
	s_cbranch_vccnz .LBB0_220
	s_andn2_b64 vcc, exec, s[10:11]
	s_cbranch_vccnz .LBB0_219
	s_barrier
	s_branch .LBB0_219

;     __device__ __forceinline__ void operator()(const f32x4 (&acc)[2][2][4][2], const pg8::Unit& u, int wr, int wc, int fr, int fq) const {
;         const int row0 = u.pm * 256 + wr * 64 + fr; const float* gp = gate + (size_t)(u.pm >> 5) * NMOD;
; #pragma unroll
;         for (int bj = 0; bj < 2; ++bj) {
;             const int col = u.pn * 256 + bj * 128 + wc * 32 + 8 * fq;
;             const f32x4 g0 = *(const f32x4*)(gp + col) * coef, g1 = *(const f32x4*)(gp + col + 4) * coef;
; #pragma unroll
;             for (int ai = 0; ai < 2; ++ai)
; #pragma unroll
;                 for (int m = 0; m < 4; ++m) {
;                     const size_t off = (size_t)(row0 + ai * 128 + m * 16) * DM + col;
;                     const f32x4 x0 = *(const f32x4*)(base + off), x1 = *(const f32x4*)(base + off + 4);
;                     *(f32x4*)(out + off) = x0 + g0 * acc[ai][bj][m][0]; *(f32x4*)(out + off + 4) = x1 + g1 * acc[ai][bj][m][1];
;                     if (m & 1) asm volatile("" ::: "memory");
;                 }
;         }
;     }
.LBB0_1173:
	v_and_b32_e32 v243, 8, v164
	v_sub_u32_e32 v240, v164, v243
	v_lshrrev_b32_e32 v243, 1, v243
	v_add_u32_e32 v241, v167, v243
	v_lshl_add_u32 v240, s28, 8, v240
	v_lshl_add_u32 v241, s53, 8, v241
	v_lshlrev_b32_e32 v240, 10, v240
	v_add_lshl_u32 v240, v240, v241, 2
	v_lshlrev_b32_e32 v241, 2, v241
	v_add_u32_e32 v242, 0x8000, v240
	s_ashr_i32 s98, s28, 5
	s_mul_i32 s98, s98, 0x9000
	s_add_u32 s98, s45, s98
	s_addc_u32 s99, s46, 0
	global_load_dwordx4 v[152:155], v241, s[98:99]
	s_add_u32 s100, s90, 0x0
	s_addc_u32 s101, s91, 0
	global_load_dwordx4 v[172:175], v240, s[100:101]
	global_load_dwordx4 v[176:179], v242, s[100:101]
	s_add_u32 s100, s90, 0x10000
	s_addc_u32 s101, s91, 0
	global_load_dwordx4 v[180:183], v240, s[100:101]
	global_load_dwordx4 v[184:187], v242, s[100:101]
	s_add_u32 s100, s90, 0x20000
	s_addc_u32 s101, s91, 0
	global_load_dwordx4 v[188:191], v240, s[100:101]
	global_load_dwordx4 v[192:195], v242, s[100:101]
	s_add_u32 s100, s90, 0x30000
	s_addc_u32 s101, s91, 0
	global_load_dwordx4 v[196:199], v240, s[100:101]
	global_load_dwordx4 v[200:203], v242, s[100:101]
	s_add_u32 s100, s90, 0x80000
	s_addc_u32 s101, s91, 0
	global_load_dwordx4 v[208:211], v240, s[100:101]
	global_load_dwordx4 v[212:215], v242, s[100:101]
	s_add_u32 s100, s90, 0x90000
	s_addc_u32 s101, s91, 0
	global_load_dwordx4 v[216:219], v240, s[100:101]
	global_load_dwordx4 v[220:223], v242, s[100:101]
	s_add_u32 s100, s90, 0xa0000
	s_addc_u32 s101, s91, 0
	global_load_dwordx4 v[224:227], v240, s[100:101]
	global_load_dwordx4 v[228:231], v242, s[100:101]
	s_add_u32 s100, s90, 0xb0000
	s_addc_u32 s101, s91, 0
	global_load_dwordx4 v[232:235], v240, s[100:101]
	global_load_dwordx4 v[236:239], v242, s[100:101]
	v_mov_b32_dpp v156, v120 row_ror:8 row_mask:0xf bank_mask:0xf
	v_mov_b32_dpp v157, v121 row_ror:8 row_mask:0xf bank_mask:0xf
	v_mov_b32_dpp v158, v122 row_ror:8 row_mask:0xf bank_mask:0xf
	v_mov_b32_dpp v159, v123 row_ror:8 row_mask:0xf bank_mask:0xf
	v_mov_b32_dpp v120, v124 row_ror:8 row_mask:0xf bank_mask:0x3
	v_mov_b32_dpp v121, v125 row_ror:8 row_mask:0xf bank_mask:0x3
	v_mov_b32_dpp v122, v126 row_ror:8 row_mask:0xf bank_mask:0x3
	v_mov_b32_dpp v123, v127 row_ror:8 row_mask:0xf bank_mask:0x3
	v_mov_b32_dpp v124, v156 quad_perm:[0,1,2,3] row_mask:0xf bank_mask:0xc
	v_mov_b32_dpp v125, v157 quad_perm:[0,1,2,3] row_mask:0xf bank_mask:0xc
	v_mov_b32_dpp v126, v158 quad_perm:[0,1,2,3] row_mask:0xf bank_mask:0xc
	v_mov_b32_dpp v127, v159 quad_perm:[0,1,2,3] row_mask:0xf bank_mask:0xc
	s_waitcnt vmcnt(16)
	s_waitcnt vmcnt(14)
	v_pk_fma_f32 v[124:125], v[124:125], v[152:153], v[172:173]
	v_pk_fma_f32 v[126:127], v[126:127], v[154:155], v[174:175]
	v_pk_fma_f32 v[120:121], v[120:121], v[152:153], v[176:177]
	v_pk_fma_f32 v[122:123], v[122:123], v[154:155], v[178:179]
	s_add_u32 s98, s90, 0x0
	s_addc_u32 s99, s91, 0
	global_store_dwordx4 v240, v[124:127], s[98:99]
	global_store_dwordx4 v242, v[120:123], s[98:99]
	s_add_u32 s100, s90, 0x0
	s_addc_u32 s101, s91, 0
	global_load_dwordx4 v[172:175], v240, s[100:101] offset:512
	global_load_dwordx4 v[176:179], v242, s[100:101] offset:512
	s_ashr_i32 s98, s28, 5
	s_mul_i32 s98, s98, 0x9000
	s_add_u32 s98, s45, s98
	s_addc_u32 s99, s46, 0
	global_load_dwordx4 v[120:123], v241, s[98:99] offset:512
	v_mov_b32_dpp v156, v112 row_ror:8 row_mask:0xf bank_mask:0xf
	v_mov_b32_dpp v157, v113 row_ror:8 row_mask:0xf bank_mask:0xf
	v_mov_b32_dpp v158, v114 row_ror:8 row_mask:0xf bank_mask:0xf
	v_mov_b32_dpp v159, v115 row_ror:8 row_mask:0xf bank_mask:0xf
	v_mov_b32_dpp v112, v116 row_ror:8 row_mask:0xf bank_mask:0x3
	v_mov_b32_dpp v113, v117 row_ror:8 row_mask:0xf bank_mask:0x3
	v_mov_b32_dpp v114, v118 row_ror:8 row_mask:0xf bank_mask:0x3
	v_mov_b32_dpp v115, v119 row_ror:8 row_mask:0xf bank_mask:0x3
	v_mov_b32_dpp v116, v156 quad_perm:[0,1,2,3] row_mask:0xf bank_mask:0xc
	v_mov_b32_dpp v117, v157 quad_perm:[0,1,2,3] row_mask:0xf bank_mask:0xc
	v_mov_b32_dpp v118, v158 quad_perm:[0,1,2,3] row_mask:0xf bank_mask:0xc
	v_mov_b32_dpp v119, v159 quad_perm:[0,1,2,3] row_mask:0xf bank_mask:0xc
	s_waitcnt vmcnt(17)
	v_pk_fma_f32 v[116:117], v[116:117], v[152:153], v[180:181]
	v_pk_fma_f32 v[118:119], v[118:119], v[154:155], v[182:183]
	v_pk_fma_f32 v[112:113], v[112:113], v[152:153], v[184:185]
	v_pk_fma_f32 v[114:115], v[114:115], v[154:155], v[186:187]
	s_add_u32 s98, s90, 0x10000
	s_addc_u32 s99, s91, 0
	global_store_dwordx4 v240, v[116:119], s[98:99]
	global_store_dwordx4 v242, v[112:115], s[98:99]
	s_add_u32 s100, s90, 0x10000
	s_addc_u32 s101, s91, 0
	global_load_dwordx4 v[180:183], v240, s[100:101] offset:512
	global_load_dwordx4 v[184:187], v242, s[100:101] offset:512
	v_mov_b32_dpp v156, v104 row_ror:8 row_mask:0xf bank_mask:0xf
	v_mov_b32_dpp v157, v105 row_ror:8 row_mask:0xf bank_mask:0xf
	v_mov_b32_dpp v158, v106 row_ror:8 row_mask:0xf bank_mask:0xf
	v_mov_b32_dpp v159, v107 row_ror:8 row_mask:0xf bank_mask:0xf
	v_mov_b32_dpp v104, v108 row_ror:8 row_mask:0xf bank_mask:0x3
	v_mov_b32_dpp v105, v109 row_ror:8 row_mask:0xf bank_mask:0x3
	v_mov_b32_dpp v106, v110 row_ror:8 row_mask:0xf bank_mask:0x3
	v_mov_b32_dpp v107, v111 row_ror:8 row_mask:0xf bank_mask:0x3
	v_mov_b32_dpp v108, v156 quad_perm:[0,1,2,3] row_mask:0xf bank_mask:0xc
	v_mov_b32_dpp v109, v157 quad_perm:[0,1,2,3] row_mask:0xf bank_mask:0xc
	v_mov_b32_dpp v110, v158 quad_perm:[0,1,2,3] row_mask:0xf bank_mask:0xc
	v_mov_b32_dpp v111, v159 quad_perm:[0,1,2,3] row_mask:0xf bank_mask:0xc
	s_waitcnt vmcnt(19)
;     __device__ __forceinline__ void operator()(const f32x4 (&acc)[2][2][4][2], const pg8::Unit& u, int wr, int wc, int fr, int fq) const {
;         const int row0 = u.pm * 256 + wr * 64 + fr; const float* gp = gate + (size_t)(u.pm >> 5) * NMOD;
; #pragma unroll
;         for (int bj = 0; bj < 2; ++bj) {
;             const int col = u.pn * 256 + bj * 128 + wc * 32 + 8 * fq;
;             const f32x4 g0 = *(const f32x4*)(gp + col) * coef, g1 = *(const f32x4*)(gp + col + 4) * coef;
; #pragma unroll
;             for (int ai = 0; ai < 2; ++ai)
; #pragma unroll
;                 for (int m = 0; m < 4; ++m) {
;                     const size_t off = (size_t)(row0 + ai * 128 + m * 16) * DM + col;
;                     const f32x4 x0 = *(const f32x4*)(base + off), x1 = *(const f32x4*)(base + off + 4);
;                     *(f32x4*)(out + off) = x0 + g0 * acc[ai][bj][m][0]; *(f32x4*)(out + off + 4) = x1 + g1 * acc[ai][bj][m][1];
;                     if (m & 1) asm volatile("" ::: "memory");
;                 }
;         }
;     }
	v_pk_fma_f32 v[108:109], v[108:109], v[152:153], v[188:189]
	v_pk_fma_f32 v[110:111], v[110:111], v[154:155], v[190:191]
	v_pk_fma_f32 v[104:105], v[104:105], v[152:153], v[192:193]
	v_pk_fma_f32 v[106:107], v[106:107], v[154:155], v[194:195]
	s_add_u32 s98, s90, 0x20000
	s_addc_u32 s99, s91, 0
	global_store_dwordx4 v240, v[108:111], s[98:99]
	global_store_dwordx4 v242, v[104:107], s[98:99]
	s_add_u32 s100, s90, 0x20000
	s_addc_u32 s101, s91, 0
	global_load_dwordx4 v[188:191], v240, s[100:101] offset:512
	global_load_dwordx4 v[192:195], v242, s[100:101] offset:512
	v_mov_b32_dpp v156, v96 row_ror:8 row_mask:0xf bank_mask:0xf
	v_mov_b32_dpp v157, v97 row_ror:8 row_mask:0xf bank_mask:0xf
	v_mov_b32_dpp v158, v98 row_ror:8 row_mask:0xf bank_mask:0xf
	v_mov_b32_dpp v159, v99 row_ror:8 row_mask:0xf bank_mask:0xf
	v_mov_b32_dpp v96, v100 row_ror:8 row_mask:0xf bank_mask:0x3
	v_mov_b32_dpp v97, v101 row_ror:8 row_mask:0xf bank_mask:0x3
	v_mov_b32_dpp v98, v102 row_ror:8 row_mask:0xf bank_mask:0x3
	v_mov_b32_dpp v99, v103 row_ror:8 row_mask:0xf bank_mask:0x3
	v_mov_b32_dpp v100, v156 quad_perm:[0,1,2,3] row_mask:0xf bank_mask:0xc
	v_mov_b32_dpp v101, v157 quad_perm:[0,1,2,3] row_mask:0xf bank_mask:0xc
	v_mov_b32_dpp v102, v158 quad_perm:[0,1,2,3] row_mask:0xf bank_mask:0xc
	v_mov_b32_dpp v103, v159 quad_perm:[0,1,2,3] row_mask:0xf bank_mask:0xc
	s_waitcnt vmcnt(21)
	v_pk_fma_f32 v[100:101], v[100:101], v[152:153], v[196:197]
	v_pk_fma_f32 v[102:103], v[102:103], v[154:155], v[198:199]
	v_pk_fma_f32 v[96:97], v[96:97], v[152:153], v[200:201]
	v_pk_fma_f32 v[98:99], v[98:99], v[154:155], v[202:203]
	s_add_u32 s98, s90, 0x30000
	s_addc_u32 s99, s91, 0
	global_store_dwordx4 v240, v[100:103], s[98:99]
	global_store_dwordx4 v242, v[96:99], s[98:99]
	s_add_u32 s100, s90, 0x30000
	s_addc_u32 s101, s91, 0
	global_load_dwordx4 v[196:199], v240, s[100:101] offset:512
	global_load_dwordx4 v[200:203], v242, s[100:101] offset:512
	v_mov_b32_dpp v156, v88 row_ror:8 row_mask:0xf bank_mask:0xf
	v_mov_b32_dpp v157, v89 row_ror:8 row_mask:0xf bank_mask:0xf
	v_mov_b32_dpp v158, v90 row_ror:8 row_mask:0xf bank_mask:0xf
	v_mov_b32_dpp v159, v91 row_ror:8 row_mask:0xf bank_mask:0xf
	v_mov_b32_dpp v88, v92 row_ror:8 row_mask:0xf bank_mask:0x3
	v_mov_b32_dpp v89, v93 row_ror:8 row_mask:0xf bank_mask:0x3
	v_mov_b32_dpp v90, v94 row_ror:8 row_mask:0xf bank_mask:0x3
	v_mov_b32_dpp v91, v95 row_ror:8 row_mask:0xf bank_mask:0x3
	v_mov_b32_dpp v92, v156 quad_perm:[0,1,2,3] row_mask:0xf bank_mask:0xc
	v_mov_b32_dpp v93, v157 quad_perm:[0,1,2,3] row_mask:0xf bank_mask:0xc
	v_mov_b32_dpp v94, v158 quad_perm:[0,1,2,3] row_mask:0xf bank_mask:0xc
	v_mov_b32_dpp v95, v159 quad_perm:[0,1,2,3] row_mask:0xf bank_mask:0xc
	s_waitcnt vmcnt(23)
	v_pk_fma_f32 v[92:93], v[92:93], v[152:153], v[208:209]
	v_pk_fma_f32 v[94:95], v[94:95], v[154:155], v[210:211]
	v_pk_fma_f32 v[88:89], v[88:89], v[152:153], v[212:213]
	v_pk_fma_f32 v[90:91], v[90:91], v[154:155], v[214:215]
	s_add_u32 s98, s90, 0x80000
	s_addc_u32 s99, s91, 0
	global_store_dwordx4 v240, v[92:95], s[98:99]
	global_store_dwordx4 v242, v[88:91], s[98:99]
	s_add_u32 s100, s90, 0x80000
	s_addc_u32 s101, s91, 0
	global_load_dwordx4 v[208:211], v240, s[100:101] offset:512
	global_load_dwordx4 v[212:215], v242, s[100:101] offset:512
	v_mov_b32_dpp v156, v80 row_ror:8 row_mask:0xf bank_mask:0xf
	v_mov_b32_dpp v157, v81 row_ror:8 row_mask:0xf bank_mask:0xf
	v_mov_b32_dpp v158, v82 row_ror:8 row_mask:0xf bank_mask:0xf
	v_mov_b32_dpp v159, v83 row_ror:8 row_mask:0xf bank_mask:0xf
	v_mov_b32_dpp v80, v84 row_ror:8 row_mask:0xf bank_mask:0x3
	v_mov_b32_dpp v81, v85 row_ror:8 row_mask:0xf bank_mask:0x3
	v_mov_b32_dpp v82, v86 row_ror:8 row_mask:0xf bank_mask:0x3
	v_mov_b32_dpp v83, v87 row_ror:8 row_mask:0xf bank_mask:0x3
	v_mov_b32_dpp v84, v156 quad_perm:[0,1,2,3] row_mask:0xf bank_mask:0xc
	v_mov_b32_dpp v85, v157 quad_perm:[0,1,2,3] row_mask:0xf bank_mask:0xc
	v_mov_b32_dpp v86, v158 quad_perm:[0,1,2,3] row_mask:0xf bank_mask:0xc
	v_mov_b32_dpp v87, v159 quad_perm:[0,1,2,3] row_mask:0xf bank_mask:0xc
	s_waitcnt vmcnt(25)
	v_pk_fma_f32 v[84:85], v[84:85], v[152:153], v[216:217]
	v_pk_fma_f32 v[86:87], v[86:87], v[154:155], v[218:219]
	v_pk_fma_f32 v[80:81], v[80:81], v[152:153], v[220:221]
	v_pk_fma_f32 v[82:83], v[82:83], v[154:155], v[222:223]
	s_add_u32 s98, s90, 0x90000
	s_addc_u32 s99, s91, 0
	global_store_dwordx4 v240, v[84:87], s[98:99]
	global_store_dwordx4 v242, v[80:83], s[98:99]
	s_add_u32 s100, s90, 0x90000
	s_addc_u32 s101, s91, 0
	global_load_dwordx4 v[216:219], v240, s[100:101] offset:512
	global_load_dwordx4 v[220:223], v242, s[100:101] offset:512
	v_mov_b32_dpp v156, v72 row_ror:8 row_mask:0xf bank_mask:0xf
	v_mov_b32_dpp v157, v73 row_ror:8 row_mask:0xf bank_mask:0xf
	v_mov_b32_dpp v158, v74 row_ror:8 row_mask:0xf bank_mask:0xf
	v_mov_b32_dpp v159, v75 row_ror:8 row_mask:0xf bank_mask:0xf
	v_mov_b32_dpp v72, v76 row_ror:8 row_mask:0xf bank_mask:0x3
	v_mov_b32_dpp v73, v77 row_ror:8 row_mask:0xf bank_mask:0x3
	v_mov_b32_dpp v74, v78 row_ror:8 row_mask:0xf bank_mask:0x3
	v_mov_b32_dpp v75, v79 row_ror:8 row_mask:0xf bank_mask:0x3
	v_mov_b32_dpp v76, v156 quad_perm:[0,1,2,3] row_mask:0xf bank_mask:0xc
	v_mov_b32_dpp v77, v157 quad_perm:[0,1,2,3] row_mask:0xf bank_mask:0xc
	v_mov_b32_dpp v78, v158 quad_perm:[0,1,2,3] row_mask:0xf bank_mask:0xc
	v_mov_b32_dpp v79, v159 quad_perm:[0,1,2,3] row_mask:0xf bank_mask:0xc
	s_waitcnt vmcnt(27)
;     __device__ __forceinline__ void operator()(const f32x4 (&acc)[2][2][4][2], const pg8::Unit& u, int wr, int wc, int fr, int fq) const {
;     ...
;         for (int bj = 0; bj < 2; ++bj) {
;             const int col = u.pn * 256 + bj * 128 + wc * 32 + 8 * fq;
;             const f32x4 g0 = *(const f32x4*)(gp + col) * coef, g1 = *(const f32x4*)(gp + col + 4) * coef;
; #pragma unroll
;             for (int ai = 0; ai < 2; ++ai)
; #pragma unroll
;                 for (int m = 0; m < 4; ++m) {
;                     const size_t off = (size_t)(row0 + ai * 128 + m * 16) * DM + col;
;                     const f32x4 x0 = *(const f32x4*)(base + off), x1 = *(const f32x4*)(base + off + 4);
;                     *(f32x4*)(out + off) = x0 + g0 * acc[ai][bj][m][0]; *(f32x4*)(out + off + 4) = x1 + g1 * acc[ai][bj][m][1];
;                     if (m & 1) asm volatile("" ::: "memory");
;                 }
	v_pk_fma_f32 v[76:77], v[76:77], v[152:153], v[224:225]
	v_pk_fma_f32 v[78:79], v[78:79], v[154:155], v[226:227]
	v_pk_fma_f32 v[72:73], v[72:73], v[152:153], v[228:229]
	v_pk_fma_f32 v[74:75], v[74:75], v[154:155], v[230:231]
	s_add_u32 s98, s90, 0xa0000
	s_addc_u32 s99, s91, 0
	global_store_dwordx4 v240, v[76:79], s[98:99]
	global_store_dwordx4 v242, v[72:75], s[98:99]
	s_add_u32 s100, s90, 0xa0000
	s_addc_u32 s101, s91, 0
	global_load_dwordx4 v[224:227], v240, s[100:101] offset:512
	global_load_dwordx4 v[228:231], v242, s[100:101] offset:512
	v_mov_b32_dpp v156, v64 row_ror:8 row_mask:0xf bank_mask:0xf
	v_mov_b32_dpp v157, v65 row_ror:8 row_mask:0xf bank_mask:0xf
	v_mov_b32_dpp v158, v66 row_ror:8 row_mask:0xf bank_mask:0xf
	v_mov_b32_dpp v159, v67 row_ror:8 row_mask:0xf bank_mask:0xf
	v_mov_b32_dpp v64, v68 row_ror:8 row_mask:0xf bank_mask:0x3
	v_mov_b32_dpp v65, v69 row_ror:8 row_mask:0xf bank_mask:0x3
	v_mov_b32_dpp v66, v70 row_ror:8 row_mask:0xf bank_mask:0x3
	v_mov_b32_dpp v67, v71 row_ror:8 row_mask:0xf bank_mask:0x3
	v_mov_b32_dpp v68, v156 quad_perm:[0,1,2,3] row_mask:0xf bank_mask:0xc
	v_mov_b32_dpp v69, v157 quad_perm:[0,1,2,3] row_mask:0xf bank_mask:0xc
	v_mov_b32_dpp v70, v158 quad_perm:[0,1,2,3] row_mask:0xf bank_mask:0xc
	v_mov_b32_dpp v71, v159 quad_perm:[0,1,2,3] row_mask:0xf bank_mask:0xc
	s_waitcnt vmcnt(29)
	v_pk_fma_f32 v[68:69], v[68:69], v[152:153], v[232:233]
	v_pk_fma_f32 v[70:71], v[70:71], v[154:155], v[234:235]
	v_pk_fma_f32 v[64:65], v[64:65], v[152:153], v[236:237]
	v_pk_fma_f32 v[66:67], v[66:67], v[154:155], v[238:239]
	s_add_u32 s98, s90, 0xb0000
	s_addc_u32 s99, s91, 0
	global_store_dwordx4 v240, v[68:71], s[98:99]
	global_store_dwordx4 v242, v[64:67], s[98:99]
	s_add_u32 s100, s90, 0xb0000
	s_addc_u32 s101, s91, 0
	global_load_dwordx4 v[232:235], v240, s[100:101] offset:512
	global_load_dwordx4 v[236:239], v242, s[100:101] offset:512
	v_mov_b32_dpp v156, v56 row_ror:8 row_mask:0xf bank_mask:0xf
	v_mov_b32_dpp v157, v57 row_ror:8 row_mask:0xf bank_mask:0xf
	v_mov_b32_dpp v158, v58 row_ror:8 row_mask:0xf bank_mask:0xf
	v_mov_b32_dpp v159, v59 row_ror:8 row_mask:0xf bank_mask:0xf
	v_mov_b32_dpp v56, v60 row_ror:8 row_mask:0xf bank_mask:0x3
	v_mov_b32_dpp v57, v61 row_ror:8 row_mask:0xf bank_mask:0x3
	v_mov_b32_dpp v58, v62 row_ror:8 row_mask:0xf bank_mask:0x3
	v_mov_b32_dpp v59, v63 row_ror:8 row_mask:0xf bank_mask:0x3
	v_mov_b32_dpp v60, v156 quad_perm:[0,1,2,3] row_mask:0xf bank_mask:0xc
	v_mov_b32_dpp v61, v157 quad_perm:[0,1,2,3] row_mask:0xf bank_mask:0xc
	v_mov_b32_dpp v62, v158 quad_perm:[0,1,2,3] row_mask:0xf bank_mask:0xc
	v_mov_b32_dpp v63, v159 quad_perm:[0,1,2,3] row_mask:0xf bank_mask:0xc
	s_waitcnt vmcnt(28)
	v_pk_fma_f32 v[60:61], v[60:61], v[120:121], v[172:173]
	v_pk_fma_f32 v[62:63], v[62:63], v[122:123], v[174:175]
	v_pk_fma_f32 v[56:57], v[56:57], v[120:121], v[176:177]
	v_pk_fma_f32 v[58:59], v[58:59], v[122:123], v[178:179]
	s_add_u32 s98, s90, 0x0
	s_addc_u32 s99, s91, 0
	global_store_dwordx4 v240, v[60:63], s[98:99] offset:512
	global_store_dwordx4 v242, v[56:59], s[98:99] offset:512
	v_mov_b32_dpp v156, v48 row_ror:8 row_mask:0xf bank_mask:0xf
	v_mov_b32_dpp v157, v49 row_ror:8 row_mask:0xf bank_mask:0xf
	v_mov_b32_dpp v158, v50 row_ror:8 row_mask:0xf bank_mask:0xf
	v_mov_b32_dpp v159, v51 row_ror:8 row_mask:0xf bank_mask:0xf
	v_mov_b32_dpp v48, v52 row_ror:8 row_mask:0xf bank_mask:0x3
	v_mov_b32_dpp v49, v53 row_ror:8 row_mask:0xf bank_mask:0x3
	v_mov_b32_dpp v50, v54 row_ror:8 row_mask:0xf bank_mask:0x3
	v_mov_b32_dpp v51, v55 row_ror:8 row_mask:0xf bank_mask:0x3
	v_mov_b32_dpp v52, v156 quad_perm:[0,1,2,3] row_mask:0xf bank_mask:0xc
	v_mov_b32_dpp v53, v157 quad_perm:[0,1,2,3] row_mask:0xf bank_mask:0xc
	v_mov_b32_dpp v54, v158 quad_perm:[0,1,2,3] row_mask:0xf bank_mask:0xc
	v_mov_b32_dpp v55, v159 quad_perm:[0,1,2,3] row_mask:0xf bank_mask:0xc
	s_waitcnt vmcnt(26)
	v_pk_fma_f32 v[52:53], v[52:53], v[120:121], v[180:181]
	v_pk_fma_f32 v[54:55], v[54:55], v[122:123], v[182:183]
	v_pk_fma_f32 v[48:49], v[48:49], v[120:121], v[184:185]
	v_pk_fma_f32 v[50:51], v[50:51], v[122:123], v[186:187]
	s_add_u32 s98, s90, 0x10000
	s_addc_u32 s99, s91, 0
	global_store_dwordx4 v240, v[52:55], s[98:99] offset:512
	global_store_dwordx4 v242, v[48:51], s[98:99] offset:512
	v_mov_b32_dpp v156, v40 row_ror:8 row_mask:0xf bank_mask:0xf
	v_mov_b32_dpp v157, v41 row_ror:8 row_mask:0xf bank_mask:0xf
	v_mov_b32_dpp v158, v42 row_ror:8 row_mask:0xf bank_mask:0xf
	v_mov_b32_dpp v159, v43 row_ror:8 row_mask:0xf bank_mask:0xf
	v_mov_b32_dpp v40, v44 row_ror:8 row_mask:0xf bank_mask:0x3
	v_mov_b32_dpp v41, v45 row_ror:8 row_mask:0xf bank_mask:0x3
	v_mov_b32_dpp v42, v46 row_ror:8 row_mask:0xf bank_mask:0x3
	v_mov_b32_dpp v43, v47 row_ror:8 row_mask:0xf bank_mask:0x3
	v_mov_b32_dpp v44, v156 quad_perm:[0,1,2,3] row_mask:0xf bank_mask:0xc
	v_mov_b32_dpp v45, v157 quad_perm:[0,1,2,3] row_mask:0xf bank_mask:0xc
	v_mov_b32_dpp v46, v158 quad_perm:[0,1,2,3] row_mask:0xf bank_mask:0xc
	v_mov_b32_dpp v47, v159 quad_perm:[0,1,2,3] row_mask:0xf bank_mask:0xc
	s_waitcnt vmcnt(24)
;     __device__ __forceinline__ void operator()(const f32x4 (&acc)[2][2][4][2], const pg8::Unit& u, int wr, int wc, int fr, int fq) const {
;     ...
;         for (int bj = 0; bj < 2; ++bj) {
;             const int col = u.pn * 256 + bj * 128 + wc * 32 + 8 * fq;
;             const f32x4 g0 = *(const f32x4*)(gp + col) * coef, g1 = *(const f32x4*)(gp + col + 4) * coef;
; #pragma unroll
;             for (int ai = 0; ai < 2; ++ai)
; #pragma unroll
;                 for (int m = 0; m < 4; ++m) {
;                     const size_t off = (size_t)(row0 + ai * 128 + m * 16) * DM + col;
;                     const f32x4 x0 = *(const f32x4*)(base + off), x1 = *(const f32x4*)(base + off + 4);
;                     *(f32x4*)(out + off) = x0 + g0 * acc[ai][bj][m][0]; *(f32x4*)(out + off + 4) = x1 + g1 * acc[ai][bj][m][1];
;                     if (m & 1) asm volatile("" ::: "memory");
;                 }
	v_pk_fma_f32 v[44:45], v[44:45], v[120:121], v[188:189]
	v_pk_fma_f32 v[46:47], v[46:47], v[122:123], v[190:191]
	v_pk_fma_f32 v[40:41], v[40:41], v[120:121], v[192:193]
	v_pk_fma_f32 v[42:43], v[42:43], v[122:123], v[194:195]
	s_add_u32 s98, s90, 0x20000
	s_addc_u32 s99, s91, 0
	global_store_dwordx4 v240, v[44:47], s[98:99] offset:512
	global_store_dwordx4 v242, v[40:43], s[98:99] offset:512
	v_mov_b32_dpp v156, v32 row_ror:8 row_mask:0xf bank_mask:0xf
	v_mov_b32_dpp v157, v33 row_ror:8 row_mask:0xf bank_mask:0xf
	v_mov_b32_dpp v158, v34 row_ror:8 row_mask:0xf bank_mask:0xf
	v_mov_b32_dpp v159, v35 row_ror:8 row_mask:0xf bank_mask:0xf
	v_mov_b32_dpp v32, v36 row_ror:8 row_mask:0xf bank_mask:0x3
	v_mov_b32_dpp v33, v37 row_ror:8 row_mask:0xf bank_mask:0x3
	v_mov_b32_dpp v34, v38 row_ror:8 row_mask:0xf bank_mask:0x3
	v_mov_b32_dpp v35, v39 row_ror:8 row_mask:0xf bank_mask:0x3
	v_mov_b32_dpp v36, v156 quad_perm:[0,1,2,3] row_mask:0xf bank_mask:0xc
	v_mov_b32_dpp v37, v157 quad_perm:[0,1,2,3] row_mask:0xf bank_mask:0xc
	v_mov_b32_dpp v38, v158 quad_perm:[0,1,2,3] row_mask:0xf bank_mask:0xc
	v_mov_b32_dpp v39, v159 quad_perm:[0,1,2,3] row_mask:0xf bank_mask:0xc
	s_waitcnt vmcnt(22)
	v_pk_fma_f32 v[36:37], v[36:37], v[120:121], v[196:197]
	v_pk_fma_f32 v[38:39], v[38:39], v[122:123], v[198:199]
	v_pk_fma_f32 v[32:33], v[32:33], v[120:121], v[200:201]
	v_pk_fma_f32 v[34:35], v[34:35], v[122:123], v[202:203]
	s_add_u32 s98, s90, 0x30000
	s_addc_u32 s99, s91, 0
	global_store_dwordx4 v240, v[36:39], s[98:99] offset:512
	global_store_dwordx4 v242, v[32:35], s[98:99] offset:512
	v_mov_b32_dpp v156, v24 row_ror:8 row_mask:0xf bank_mask:0xf
	v_mov_b32_dpp v157, v25 row_ror:8 row_mask:0xf bank_mask:0xf
	v_mov_b32_dpp v158, v26 row_ror:8 row_mask:0xf bank_mask:0xf
	v_mov_b32_dpp v159, v27 row_ror:8 row_mask:0xf bank_mask:0xf
	v_mov_b32_dpp v24, v28 row_ror:8 row_mask:0xf bank_mask:0x3
	v_mov_b32_dpp v25, v29 row_ror:8 row_mask:0xf bank_mask:0x3
	v_mov_b32_dpp v26, v30 row_ror:8 row_mask:0xf bank_mask:0x3
	v_mov_b32_dpp v27, v31 row_ror:8 row_mask:0xf bank_mask:0x3
	v_mov_b32_dpp v28, v156 quad_perm:[0,1,2,3] row_mask:0xf bank_mask:0xc
	v_mov_b32_dpp v29, v157 quad_perm:[0,1,2,3] row_mask:0xf bank_mask:0xc
	v_mov_b32_dpp v30, v158 quad_perm:[0,1,2,3] row_mask:0xf bank_mask:0xc
	v_mov_b32_dpp v31, v159 quad_perm:[0,1,2,3] row_mask:0xf bank_mask:0xc
	s_waitcnt vmcnt(20)
	v_pk_fma_f32 v[28:29], v[28:29], v[120:121], v[208:209]
	v_pk_fma_f32 v[30:31], v[30:31], v[122:123], v[210:211]
	v_pk_fma_f32 v[24:25], v[24:25], v[120:121], v[212:213]
	v_pk_fma_f32 v[26:27], v[26:27], v[122:123], v[214:215]
	s_add_u32 s98, s90, 0x80000
	s_addc_u32 s99, s91, 0
	global_store_dwordx4 v240, v[28:31], s[98:99] offset:512
	global_store_dwordx4 v242, v[24:27], s[98:99] offset:512
	v_mov_b32_dpp v156, v16 row_ror:8 row_mask:0xf bank_mask:0xf
	v_mov_b32_dpp v157, v17 row_ror:8 row_mask:0xf bank_mask:0xf
	v_mov_b32_dpp v158, v18 row_ror:8 row_mask:0xf bank_mask:0xf
	v_mov_b32_dpp v159, v19 row_ror:8 row_mask:0xf bank_mask:0xf
	v_mov_b32_dpp v16, v20 row_ror:8 row_mask:0xf bank_mask:0x3
	v_mov_b32_dpp v17, v21 row_ror:8 row_mask:0xf bank_mask:0x3
	v_mov_b32_dpp v18, v22 row_ror:8 row_mask:0xf bank_mask:0x3
	v_mov_b32_dpp v19, v23 row_ror:8 row_mask:0xf bank_mask:0x3
	v_mov_b32_dpp v20, v156 quad_perm:[0,1,2,3] row_mask:0xf bank_mask:0xc
	v_mov_b32_dpp v21, v157 quad_perm:[0,1,2,3] row_mask:0xf bank_mask:0xc
	v_mov_b32_dpp v22, v158 quad_perm:[0,1,2,3] row_mask:0xf bank_mask:0xc
	v_mov_b32_dpp v23, v159 quad_perm:[0,1,2,3] row_mask:0xf bank_mask:0xc
	s_waitcnt vmcnt(18)
	v_pk_fma_f32 v[20:21], v[20:21], v[120:121], v[216:217]
	v_pk_fma_f32 v[22:23], v[22:23], v[122:123], v[218:219]
	v_pk_fma_f32 v[16:17], v[16:17], v[120:121], v[220:221]
	v_pk_fma_f32 v[18:19], v[18:19], v[122:123], v[222:223]
	s_add_u32 s98, s90, 0x90000
	s_addc_u32 s99, s91, 0
	global_store_dwordx4 v240, v[20:23], s[98:99] offset:512
	global_store_dwordx4 v242, v[16:19], s[98:99] offset:512
	v_mov_b32_dpp v156, v8 row_ror:8 row_mask:0xf bank_mask:0xf
	v_mov_b32_dpp v157, v9 row_ror:8 row_mask:0xf bank_mask:0xf
	v_mov_b32_dpp v158, v10 row_ror:8 row_mask:0xf bank_mask:0xf
	v_mov_b32_dpp v159, v11 row_ror:8 row_mask:0xf bank_mask:0xf
	v_mov_b32_dpp v8, v12 row_ror:8 row_mask:0xf bank_mask:0x3
	v_mov_b32_dpp v9, v13 row_ror:8 row_mask:0xf bank_mask:0x3
	v_mov_b32_dpp v10, v14 row_ror:8 row_mask:0xf bank_mask:0x3
	v_mov_b32_dpp v11, v15 row_ror:8 row_mask:0xf bank_mask:0x3
	v_mov_b32_dpp v12, v156 quad_perm:[0,1,2,3] row_mask:0xf bank_mask:0xc
	v_mov_b32_dpp v13, v157 quad_perm:[0,1,2,3] row_mask:0xf bank_mask:0xc
	v_mov_b32_dpp v14, v158 quad_perm:[0,1,2,3] row_mask:0xf bank_mask:0xc
	v_mov_b32_dpp v15, v159 quad_perm:[0,1,2,3] row_mask:0xf bank_mask:0xc
	s_waitcnt vmcnt(16)
	v_pk_fma_f32 v[12:13], v[12:13], v[120:121], v[224:225]
	v_pk_fma_f32 v[14:15], v[14:15], v[122:123], v[226:227]
	v_pk_fma_f32 v[8:9], v[8:9], v[120:121], v[228:229]
	v_pk_fma_f32 v[10:11], v[10:11], v[122:123], v[230:231]
	s_add_u32 s98, s90, 0xa0000
	s_addc_u32 s99, s91, 0
	global_store_dwordx4 v240, v[12:15], s[98:99] offset:512
	global_store_dwordx4 v242, v[8:11], s[98:99] offset:512
	v_mov_b32_dpp v156, v0 row_ror:8 row_mask:0xf bank_mask:0xf
	v_mov_b32_dpp v157, v1 row_ror:8 row_mask:0xf bank_mask:0xf
	v_mov_b32_dpp v158, v2 row_ror:8 row_mask:0xf bank_mask:0xf
	v_mov_b32_dpp v159, v3 row_ror:8 row_mask:0xf bank_mask:0xf
	v_mov_b32_dpp v0, v4 row_ror:8 row_mask:0xf bank_mask:0x3
	v_mov_b32_dpp v1, v5 row_ror:8 row_mask:0xf bank_mask:0x3
	v_mov_b32_dpp v2, v6 row_ror:8 row_mask:0xf bank_mask:0x3
	v_mov_b32_dpp v3, v7 row_ror:8 row_mask:0xf bank_mask:0x3
	v_mov_b32_dpp v4, v156 quad_perm:[0,1,2,3] row_mask:0xf bank_mask:0xc
	v_mov_b32_dpp v5, v157 quad_perm:[0,1,2,3] row_mask:0xf bank_mask:0xc
	v_mov_b32_dpp v6, v158 quad_perm:[0,1,2,3] row_mask:0xf bank_mask:0xc
	v_mov_b32_dpp v7, v159 quad_perm:[0,1,2,3] row_mask:0xf bank_mask:0xc
	s_waitcnt vmcnt(14)
	v_pk_fma_f32 v[4:5], v[4:5], v[120:121], v[232:233]
	v_pk_fma_f32 v[6:7], v[6:7], v[122:123], v[234:235]
	v_pk_fma_f32 v[0:1], v[0:1], v[120:121], v[236:237]
	v_pk_fma_f32 v[2:3], v[2:3], v[122:123], v[238:239]
	s_add_u32 s98, s90, 0xb0000
	s_addc_u32 s99, s91, 0
	global_store_dwordx4 v240, v[4:7], s[98:99] offset:512
	global_store_dwordx4 v242, v[0:3], s[98:99] offset:512
	s_andn2_b64 vcc, exec, s[6:7]
	s_mov_b64 s[6:7], -1
	s_cbranch_vccnz .LBB0_1162
	s_andn2_b64 vcc, exec, s[0:1]
	s_cbranch_vccnz .LBB0_1161
	s_barrier
	s_branch .LBB0_1161

;     __device__ __forceinline__ void operator()(const f32x4 (&acc)[2][2][4][2], const pg8::Unit& u, int wr, int wc, int fr, int fq) const {
;         const int row0 = u.pm * 256 + wr * 64 + fr; const float* gp = gate + (size_t)(u.pm >> 5) * NMOD;
; #pragma unroll
;         for (int bj = 0; bj < 2; ++bj) {
;             const int col = u.pn * 256 + bj * 128 + wc * 32 + 8 * fq;
;             const f32x4 g0 = *(const f32x4*)(gp + col) * coef, g1 = *(const f32x4*)(gp + col + 4) * coef;
; #pragma unroll
;             for (int ai = 0; ai < 2; ++ai)
; #pragma unroll
;                 for (int m = 0; m < 4; ++m) {
;                     const size_t off = (size_t)(row0 + ai * 128 + m * 16) * DM + col;
;                     const f32x4 x0 = *(const f32x4*)(base + off), x1 = *(const f32x4*)(base + off + 4);
;                     *(f32x4*)(out + off) = x0 + g0 * acc[ai][bj][m][0]; *(f32x4*)(out + off + 4) = x1 + g1 * acc[ai][bj][m][1];
;                     if (m & 1) asm volatile("" ::: "memory");
;                 }
.LBB0_1396:
	v_and_b32_e32 v243, 8, v156
	v_sub_u32_e32 v240, v156, v243
	v_lshrrev_b32_e32 v243, 1, v243
	v_add_u32_e32 v241, v158, v243
	v_lshl_add_u32 v240, s47, 8, v240
	v_lshl_add_u32 v241, s48, 8, v241
	v_lshlrev_b32_e32 v240, 10, v240
	v_add_lshl_u32 v240, v240, v241, 2
	v_lshlrev_b32_e32 v241, 2, v241
	v_add_u32_e32 v242, 0x8000, v240
	s_ashr_i32 s98, s47, 5
	s_mul_i32 s98, s98, 0x9000
	s_add_u32 s98, s38, s98
	s_addc_u32 s99, s39, 0
	global_load_dwordx4 v[144:147], v241, s[98:99]
	s_add_u32 s100, s90, 0x0
	s_addc_u32 s101, s91, 0
	global_load_dwordx4 v[172:175], v240, s[100:101]
	global_load_dwordx4 v[176:179], v242, s[100:101]
	s_add_u32 s100, s90, 0x10000
	s_addc_u32 s101, s91, 0
	global_load_dwordx4 v[180:183], v240, s[100:101]
	global_load_dwordx4 v[184:187], v242, s[100:101]
	s_add_u32 s100, s90, 0x20000
	s_addc_u32 s101, s91, 0
	global_load_dwordx4 v[188:191], v240, s[100:101]
	global_load_dwordx4 v[192:195], v242, s[100:101]
	s_add_u32 s100, s90, 0x30000
	s_addc_u32 s101, s91, 0
	global_load_dwordx4 v[196:199], v240, s[100:101]
	global_load_dwordx4 v[200:203], v242, s[100:101]
	s_add_u32 s100, s90, 0x80000
	s_addc_u32 s101, s91, 0
	global_load_dwordx4 v[208:211], v240, s[100:101]
	global_load_dwordx4 v[212:215], v242, s[100:101]
	s_add_u32 s100, s90, 0x90000
	s_addc_u32 s101, s91, 0
	global_load_dwordx4 v[216:219], v240, s[100:101]
	global_load_dwordx4 v[220:223], v242, s[100:101]
	s_add_u32 s100, s90, 0xa0000
	s_addc_u32 s101, s91, 0
	global_load_dwordx4 v[224:227], v240, s[100:101]
	global_load_dwordx4 v[228:231], v242, s[100:101]
	s_add_u32 s100, s90, 0xb0000
	s_addc_u32 s101, s91, 0
	global_load_dwordx4 v[232:235], v240, s[100:101]
	global_load_dwordx4 v[236:239], v242, s[100:101]
	v_mov_b32_dpp v148, v120 row_ror:8 row_mask:0xf bank_mask:0xf
	v_mov_b32_dpp v149, v121 row_ror:8 row_mask:0xf bank_mask:0xf
	v_mov_b32_dpp v150, v122 row_ror:8 row_mask:0xf bank_mask:0xf
	v_mov_b32_dpp v151, v123 row_ror:8 row_mask:0xf bank_mask:0xf
	v_mov_b32_dpp v120, v124 row_ror:8 row_mask:0xf bank_mask:0x3
	v_mov_b32_dpp v121, v125 row_ror:8 row_mask:0xf bank_mask:0x3
	v_mov_b32_dpp v122, v126 row_ror:8 row_mask:0xf bank_mask:0x3
	v_mov_b32_dpp v123, v127 row_ror:8 row_mask:0xf bank_mask:0x3
	v_mov_b32_dpp v124, v148 quad_perm:[0,1,2,3] row_mask:0xf bank_mask:0xc
	v_mov_b32_dpp v125, v149 quad_perm:[0,1,2,3] row_mask:0xf bank_mask:0xc
	v_mov_b32_dpp v126, v150 quad_perm:[0,1,2,3] row_mask:0xf bank_mask:0xc
	v_mov_b32_dpp v127, v151 quad_perm:[0,1,2,3] row_mask:0xf bank_mask:0xc
	s_waitcnt vmcnt(16)
	v_pk_mul_f32 v[144:145], v[144:145], 0.5 op_sel_hi:[1,0]
	v_pk_mul_f32 v[146:147], v[146:147], 0.5 op_sel_hi:[1,0]
	s_waitcnt vmcnt(14)
	v_pk_fma_f32 v[124:125], v[124:125], v[144:145], v[172:173]
	v_pk_fma_f32 v[126:127], v[126:127], v[146:147], v[174:175]
	v_pk_fma_f32 v[120:121], v[120:121], v[144:145], v[176:177]
	v_pk_fma_f32 v[122:123], v[122:123], v[146:147], v[178:179]
	s_add_u32 s98, s90, 0x0
	s_addc_u32 s99, s91, 0
	global_store_dwordx4 v240, v[124:127], s[98:99]
	global_store_dwordx4 v242, v[120:123], s[98:99]
	s_add_u32 s100, s90, 0x0
	s_addc_u32 s101, s91, 0
	global_load_dwordx4 v[172:175], v240, s[100:101] offset:512
	global_load_dwordx4 v[176:179], v242, s[100:101] offset:512
	s_ashr_i32 s98, s47, 5
	s_mul_i32 s98, s98, 0x9000
	s_add_u32 s98, s38, s98
	s_addc_u32 s99, s39, 0
	global_load_dwordx4 v[120:123], v241, s[98:99] offset:512
	v_mov_b32_dpp v148, v112 row_ror:8 row_mask:0xf bank_mask:0xf
	v_mov_b32_dpp v149, v113 row_ror:8 row_mask:0xf bank_mask:0xf
	v_mov_b32_dpp v150, v114 row_ror:8 row_mask:0xf bank_mask:0xf
	v_mov_b32_dpp v151, v115 row_ror:8 row_mask:0xf bank_mask:0xf
	v_mov_b32_dpp v112, v116 row_ror:8 row_mask:0xf bank_mask:0x3
	v_mov_b32_dpp v113, v117 row_ror:8 row_mask:0xf bank_mask:0x3
	v_mov_b32_dpp v114, v118 row_ror:8 row_mask:0xf bank_mask:0x3
	v_mov_b32_dpp v115, v119 row_ror:8 row_mask:0xf bank_mask:0x3
	v_mov_b32_dpp v116, v148 quad_perm:[0,1,2,3] row_mask:0xf bank_mask:0xc
	v_mov_b32_dpp v117, v149 quad_perm:[0,1,2,3] row_mask:0xf bank_mask:0xc
	v_mov_b32_dpp v118, v150 quad_perm:[0,1,2,3] row_mask:0xf bank_mask:0xc
	v_mov_b32_dpp v119, v151 quad_perm:[0,1,2,3] row_mask:0xf bank_mask:0xc
	s_waitcnt vmcnt(17)
	v_pk_fma_f32 v[116:117], v[116:117], v[144:145], v[180:181]
	v_pk_fma_f32 v[118:119], v[118:119], v[146:147], v[182:183]
	v_pk_fma_f32 v[112:113], v[112:113], v[144:145], v[184:185]
	v_pk_fma_f32 v[114:115], v[114:115], v[146:147], v[186:187]
	s_add_u32 s98, s90, 0x10000
	s_addc_u32 s99, s91, 0
	global_store_dwordx4 v240, v[116:119], s[98:99]
	global_store_dwordx4 v242, v[112:115], s[98:99]
	s_add_u32 s100, s90, 0x10000
	s_addc_u32 s101, s91, 0
	global_load_dwordx4 v[180:183], v240, s[100:101] offset:512
	global_load_dwordx4 v[184:187], v242, s[100:101] offset:512
	v_mov_b32_dpp v148, v104 row_ror:8 row_mask:0xf bank_mask:0xf
	v_mov_b32_dpp v149, v105 row_ror:8 row_mask:0xf bank_mask:0xf
	v_mov_b32_dpp v150, v106 row_ror:8 row_mask:0xf bank_mask:0xf
	v_mov_b32_dpp v151, v107 row_ror:8 row_mask:0xf bank_mask:0xf
	v_mov_b32_dpp v104, v108 row_ror:8 row_mask:0xf bank_mask:0x3
	v_mov_b32_dpp v105, v109 row_ror:8 row_mask:0xf bank_mask:0x3
	v_mov_b32_dpp v106, v110 row_ror:8 row_mask:0xf bank_mask:0x3
	v_mov_b32_dpp v107, v111 row_ror:8 row_mask:0xf bank_mask:0x3
	v_mov_b32_dpp v108, v148 quad_perm:[0,1,2,3] row_mask:0xf bank_mask:0xc
	v_mov_b32_dpp v109, v149 quad_perm:[0,1,2,3] row_mask:0xf bank_mask:0xc
	v_mov_b32_dpp v110, v150 quad_perm:[0,1,2,3] row_mask:0xf bank_mask:0xc
	v_mov_b32_dpp v111, v151 quad_perm:[0,1,2,3] row_mask:0xf bank_mask:0xc
	s_waitcnt vmcnt(19)
;     __device__ __forceinline__ void operator()(const f32x4 (&acc)[2][2][4][2], const pg8::Unit& u, int wr, int wc, int fr, int fq) const {
;     ...
;         for (int bj = 0; bj < 2; ++bj) {
;             const int col = u.pn * 256 + bj * 128 + wc * 32 + 8 * fq;
;             const f32x4 g0 = *(const f32x4*)(gp + col) * coef, g1 = *(const f32x4*)(gp + col + 4) * coef;
; #pragma unroll
;             for (int ai = 0; ai < 2; ++ai)
; #pragma unroll
;                 for (int m = 0; m < 4; ++m) {
;                     const size_t off = (size_t)(row0 + ai * 128 + m * 16) * DM + col;
;                     const f32x4 x0 = *(const f32x4*)(base + off), x1 = *(const f32x4*)(base + off + 4);
;                     *(f32x4*)(out + off) = x0 + g0 * acc[ai][bj][m][0]; *(f32x4*)(out + off + 4) = x1 + g1 * acc[ai][bj][m][1];
;                     if (m & 1) asm volatile("" ::: "memory");
;                 }
	v_pk_fma_f32 v[108:109], v[108:109], v[144:145], v[188:189]
	v_pk_fma_f32 v[110:111], v[110:111], v[146:147], v[190:191]
	v_pk_fma_f32 v[104:105], v[104:105], v[144:145], v[192:193]
	v_pk_fma_f32 v[106:107], v[106:107], v[146:147], v[194:195]
	s_add_u32 s98, s90, 0x20000
	s_addc_u32 s99, s91, 0
	global_store_dwordx4 v240, v[108:111], s[98:99]
	global_store_dwordx4 v242, v[104:107], s[98:99]
	s_add_u32 s100, s90, 0x20000
	s_addc_u32 s101, s91, 0
	global_load_dwordx4 v[188:191], v240, s[100:101] offset:512
	global_load_dwordx4 v[192:195], v242, s[100:101] offset:512
	v_mov_b32_dpp v148, v96 row_ror:8 row_mask:0xf bank_mask:0xf
	v_mov_b32_dpp v149, v97 row_ror:8 row_mask:0xf bank_mask:0xf
	v_mov_b32_dpp v150, v98 row_ror:8 row_mask:0xf bank_mask:0xf
	v_mov_b32_dpp v151, v99 row_ror:8 row_mask:0xf bank_mask:0xf
	v_mov_b32_dpp v96, v100 row_ror:8 row_mask:0xf bank_mask:0x3
	v_mov_b32_dpp v97, v101 row_ror:8 row_mask:0xf bank_mask:0x3
	v_mov_b32_dpp v98, v102 row_ror:8 row_mask:0xf bank_mask:0x3
	v_mov_b32_dpp v99, v103 row_ror:8 row_mask:0xf bank_mask:0x3
	v_mov_b32_dpp v100, v148 quad_perm:[0,1,2,3] row_mask:0xf bank_mask:0xc
	v_mov_b32_dpp v101, v149 quad_perm:[0,1,2,3] row_mask:0xf bank_mask:0xc
	v_mov_b32_dpp v102, v150 quad_perm:[0,1,2,3] row_mask:0xf bank_mask:0xc
	v_mov_b32_dpp v103, v151 quad_perm:[0,1,2,3] row_mask:0xf bank_mask:0xc
	s_waitcnt vmcnt(21)
	v_pk_fma_f32 v[100:101], v[100:101], v[144:145], v[196:197]
	v_pk_fma_f32 v[102:103], v[102:103], v[146:147], v[198:199]
	v_pk_fma_f32 v[96:97], v[96:97], v[144:145], v[200:201]
	v_pk_fma_f32 v[98:99], v[98:99], v[146:147], v[202:203]
	s_add_u32 s98, s90, 0x30000
	s_addc_u32 s99, s91, 0
	global_store_dwordx4 v240, v[100:103], s[98:99]
	global_store_dwordx4 v242, v[96:99], s[98:99]
	s_add_u32 s100, s90, 0x30000
	s_addc_u32 s101, s91, 0
	global_load_dwordx4 v[196:199], v240, s[100:101] offset:512
	global_load_dwordx4 v[200:203], v242, s[100:101] offset:512
	v_mov_b32_dpp v148, v88 row_ror:8 row_mask:0xf bank_mask:0xf
	v_mov_b32_dpp v149, v89 row_ror:8 row_mask:0xf bank_mask:0xf
	v_mov_b32_dpp v150, v90 row_ror:8 row_mask:0xf bank_mask:0xf
	v_mov_b32_dpp v151, v91 row_ror:8 row_mask:0xf bank_mask:0xf
	v_mov_b32_dpp v88, v92 row_ror:8 row_mask:0xf bank_mask:0x3
	v_mov_b32_dpp v89, v93 row_ror:8 row_mask:0xf bank_mask:0x3
	v_mov_b32_dpp v90, v94 row_ror:8 row_mask:0xf bank_mask:0x3
	v_mov_b32_dpp v91, v95 row_ror:8 row_mask:0xf bank_mask:0x3
	v_mov_b32_dpp v92, v148 quad_perm:[0,1,2,3] row_mask:0xf bank_mask:0xc
	v_mov_b32_dpp v93, v149 quad_perm:[0,1,2,3] row_mask:0xf bank_mask:0xc
	v_mov_b32_dpp v94, v150 quad_perm:[0,1,2,3] row_mask:0xf bank_mask:0xc
	v_mov_b32_dpp v95, v151 quad_perm:[0,1,2,3] row_mask:0xf bank_mask:0xc
	s_waitcnt vmcnt(23)
	v_pk_fma_f32 v[92:93], v[92:93], v[144:145], v[208:209]
	v_pk_fma_f32 v[94:95], v[94:95], v[146:147], v[210:211]
	v_pk_fma_f32 v[88:89], v[88:89], v[144:145], v[212:213]
	v_pk_fma_f32 v[90:91], v[90:91], v[146:147], v[214:215]
	s_add_u32 s98, s90, 0x80000
	s_addc_u32 s99, s91, 0
	global_store_dwordx4 v240, v[92:95], s[98:99]
	global_store_dwordx4 v242, v[88:91], s[98:99]
	s_add_u32 s100, s90, 0x80000
	s_addc_u32 s101, s91, 0
	global_load_dwordx4 v[208:211], v240, s[100:101] offset:512
	global_load_dwordx4 v[212:215], v242, s[100:101] offset:512
	v_mov_b32_dpp v148, v80 row_ror:8 row_mask:0xf bank_mask:0xf
	v_mov_b32_dpp v149, v81 row_ror:8 row_mask:0xf bank_mask:0xf
	v_mov_b32_dpp v150, v82 row_ror:8 row_mask:0xf bank_mask:0xf
	v_mov_b32_dpp v151, v83 row_ror:8 row_mask:0xf bank_mask:0xf
	v_mov_b32_dpp v80, v84 row_ror:8 row_mask:0xf bank_mask:0x3
	v_mov_b32_dpp v81, v85 row_ror:8 row_mask:0xf bank_mask:0x3
	v_mov_b32_dpp v82, v86 row_ror:8 row_mask:0xf bank_mask:0x3
	v_mov_b32_dpp v83, v87 row_ror:8 row_mask:0xf bank_mask:0x3
	v_mov_b32_dpp v84, v148 quad_perm:[0,1,2,3] row_mask:0xf bank_mask:0xc
	v_mov_b32_dpp v85, v149 quad_perm:[0,1,2,3] row_mask:0xf bank_mask:0xc
	v_mov_b32_dpp v86, v150 quad_perm:[0,1,2,3] row_mask:0xf bank_mask:0xc
	v_mov_b32_dpp v87, v151 quad_perm:[0,1,2,3] row_mask:0xf bank_mask:0xc
	s_waitcnt vmcnt(25)
	v_pk_fma_f32 v[84:85], v[84:85], v[144:145], v[216:217]
	v_pk_fma_f32 v[86:87], v[86:87], v[146:147], v[218:219]
	v_pk_fma_f32 v[80:81], v[80:81], v[144:145], v[220:221]
	v_pk_fma_f32 v[82:83], v[82:83], v[146:147], v[222:223]
	s_add_u32 s98, s90, 0x90000
	s_addc_u32 s99, s91, 0
	global_store_dwordx4 v240, v[84:87], s[98:99]
	global_store_dwordx4 v242, v[80:83], s[98:99]
	s_add_u32 s100, s90, 0x90000
	s_addc_u32 s101, s91, 0
	global_load_dwordx4 v[216:219], v240, s[100:101] offset:512
	global_load_dwordx4 v[220:223], v242, s[100:101] offset:512
	v_mov_b32_dpp v148, v72 row_ror:8 row_mask:0xf bank_mask:0xf
	v_mov_b32_dpp v149, v73 row_ror:8 row_mask:0xf bank_mask:0xf
	v_mov_b32_dpp v150, v74 row_ror:8 row_mask:0xf bank_mask:0xf
	v_mov_b32_dpp v151, v75 row_ror:8 row_mask:0xf bank_mask:0xf
	v_mov_b32_dpp v72, v76 row_ror:8 row_mask:0xf bank_mask:0x3
	v_mov_b32_dpp v73, v77 row_ror:8 row_mask:0xf bank_mask:0x3
	v_mov_b32_dpp v74, v78 row_ror:8 row_mask:0xf bank_mask:0x3
	v_mov_b32_dpp v75, v79 row_ror:8 row_mask:0xf bank_mask:0x3
	v_mov_b32_dpp v76, v148 quad_perm:[0,1,2,3] row_mask:0xf bank_mask:0xc
	v_mov_b32_dpp v77, v149 quad_perm:[0,1,2,3] row_mask:0xf bank_mask:0xc
	v_mov_b32_dpp v78, v150 quad_perm:[0,1,2,3] row_mask:0xf bank_mask:0xc
	v_mov_b32_dpp v79, v151 quad_perm:[0,1,2,3] row_mask:0xf bank_mask:0xc
	s_waitcnt vmcnt(27)
;     __device__ __forceinline__ void operator()(const f32x4 (&acc)[2][2][4][2], const pg8::Unit& u, int wr, int wc, int fr, int fq) const {
;     ...
;         for (int bj = 0; bj < 2; ++bj) {
;             const int col = u.pn * 256 + bj * 128 + wc * 32 + 8 * fq;
;             const f32x4 g0 = *(const f32x4*)(gp + col) * coef, g1 = *(const f32x4*)(gp + col + 4) * coef;
; #pragma unroll
;             for (int ai = 0; ai < 2; ++ai)
; #pragma unroll
;                 for (int m = 0; m < 4; ++m) {
;                     const size_t off = (size_t)(row0 + ai * 128 + m * 16) * DM + col;
;                     const f32x4 x0 = *(const f32x4*)(base + off), x1 = *(const f32x4*)(base + off + 4);
;                     *(f32x4*)(out + off) = x0 + g0 * acc[ai][bj][m][0]; *(f32x4*)(out + off + 4) = x1 + g1 * acc[ai][bj][m][1];
;                     if (m & 1) asm volatile("" ::: "memory");
;                 }
	v_pk_fma_f32 v[76:77], v[76:77], v[144:145], v[224:225]
	v_pk_fma_f32 v[78:79], v[78:79], v[146:147], v[226:227]
	v_pk_fma_f32 v[72:73], v[72:73], v[144:145], v[228:229]
	v_pk_fma_f32 v[74:75], v[74:75], v[146:147], v[230:231]
	s_add_u32 s98, s90, 0xa0000
	s_addc_u32 s99, s91, 0
	global_store_dwordx4 v240, v[76:79], s[98:99]
	global_store_dwordx4 v242, v[72:75], s[98:99]
	s_add_u32 s100, s90, 0xa0000
	s_addc_u32 s101, s91, 0
	global_load_dwordx4 v[224:227], v240, s[100:101] offset:512
	global_load_dwordx4 v[228:231], v242, s[100:101] offset:512
	v_mov_b32_dpp v148, v64 row_ror:8 row_mask:0xf bank_mask:0xf
	v_mov_b32_dpp v149, v65 row_ror:8 row_mask:0xf bank_mask:0xf
	v_mov_b32_dpp v150, v66 row_ror:8 row_mask:0xf bank_mask:0xf
	v_mov_b32_dpp v151, v67 row_ror:8 row_mask:0xf bank_mask:0xf
	v_mov_b32_dpp v64, v68 row_ror:8 row_mask:0xf bank_mask:0x3
	v_mov_b32_dpp v65, v69 row_ror:8 row_mask:0xf bank_mask:0x3
	v_mov_b32_dpp v66, v70 row_ror:8 row_mask:0xf bank_mask:0x3
	v_mov_b32_dpp v67, v71 row_ror:8 row_mask:0xf bank_mask:0x3
	v_mov_b32_dpp v68, v148 quad_perm:[0,1,2,3] row_mask:0xf bank_mask:0xc
	v_mov_b32_dpp v69, v149 quad_perm:[0,1,2,3] row_mask:0xf bank_mask:0xc
	v_mov_b32_dpp v70, v150 quad_perm:[0,1,2,3] row_mask:0xf bank_mask:0xc
	v_mov_b32_dpp v71, v151 quad_perm:[0,1,2,3] row_mask:0xf bank_mask:0xc
	s_waitcnt vmcnt(29)
	v_pk_fma_f32 v[68:69], v[68:69], v[144:145], v[232:233]
	v_pk_fma_f32 v[70:71], v[70:71], v[146:147], v[234:235]
	v_pk_fma_f32 v[64:65], v[64:65], v[144:145], v[236:237]
	v_pk_fma_f32 v[66:67], v[66:67], v[146:147], v[238:239]
	s_add_u32 s98, s90, 0xb0000
	s_addc_u32 s99, s91, 0
	global_store_dwordx4 v240, v[68:71], s[98:99]
	global_store_dwordx4 v242, v[64:67], s[98:99]
	s_add_u32 s100, s90, 0xb0000
	s_addc_u32 s101, s91, 0
	global_load_dwordx4 v[232:235], v240, s[100:101] offset:512
	global_load_dwordx4 v[236:239], v242, s[100:101] offset:512
	v_mov_b32_dpp v148, v56 row_ror:8 row_mask:0xf bank_mask:0xf
	v_mov_b32_dpp v149, v57 row_ror:8 row_mask:0xf bank_mask:0xf
	v_mov_b32_dpp v150, v58 row_ror:8 row_mask:0xf bank_mask:0xf
	v_mov_b32_dpp v151, v59 row_ror:8 row_mask:0xf bank_mask:0xf
	v_mov_b32_dpp v56, v60 row_ror:8 row_mask:0xf bank_mask:0x3
	v_mov_b32_dpp v57, v61 row_ror:8 row_mask:0xf bank_mask:0x3
	v_mov_b32_dpp v58, v62 row_ror:8 row_mask:0xf bank_mask:0x3
	v_mov_b32_dpp v59, v63 row_ror:8 row_mask:0xf bank_mask:0x3
	v_mov_b32_dpp v60, v148 quad_perm:[0,1,2,3] row_mask:0xf bank_mask:0xc
	v_mov_b32_dpp v61, v149 quad_perm:[0,1,2,3] row_mask:0xf bank_mask:0xc
	v_mov_b32_dpp v62, v150 quad_perm:[0,1,2,3] row_mask:0xf bank_mask:0xc
	v_mov_b32_dpp v63, v151 quad_perm:[0,1,2,3] row_mask:0xf bank_mask:0xc
	s_waitcnt vmcnt(28)
	v_pk_mul_f32 v[120:121], v[120:121], 0.5 op_sel_hi:[1,0]
	v_pk_mul_f32 v[122:123], v[122:123], 0.5 op_sel_hi:[1,0]
	v_pk_fma_f32 v[60:61], v[60:61], v[120:121], v[172:173]
	v_pk_fma_f32 v[62:63], v[62:63], v[122:123], v[174:175]
	v_pk_fma_f32 v[56:57], v[56:57], v[120:121], v[176:177]
	v_pk_fma_f32 v[58:59], v[58:59], v[122:123], v[178:179]
	s_add_u32 s98, s90, 0x0
	s_addc_u32 s99, s91, 0
	global_store_dwordx4 v240, v[60:63], s[98:99] offset:512
	global_store_dwordx4 v242, v[56:59], s[98:99] offset:512
	v_mov_b32_dpp v148, v48 row_ror:8 row_mask:0xf bank_mask:0xf
	v_mov_b32_dpp v149, v49 row_ror:8 row_mask:0xf bank_mask:0xf
	v_mov_b32_dpp v150, v50 row_ror:8 row_mask:0xf bank_mask:0xf
	v_mov_b32_dpp v151, v51 row_ror:8 row_mask:0xf bank_mask:0xf
	v_mov_b32_dpp v48, v52 row_ror:8 row_mask:0xf bank_mask:0x3
	v_mov_b32_dpp v49, v53 row_ror:8 row_mask:0xf bank_mask:0x3
	v_mov_b32_dpp v50, v54 row_ror:8 row_mask:0xf bank_mask:0x3
	v_mov_b32_dpp v51, v55 row_ror:8 row_mask:0xf bank_mask:0x3
	v_mov_b32_dpp v52, v148 quad_perm:[0,1,2,3] row_mask:0xf bank_mask:0xc
	v_mov_b32_dpp v53, v149 quad_perm:[0,1,2,3] row_mask:0xf bank_mask:0xc
	v_mov_b32_dpp v54, v150 quad_perm:[0,1,2,3] row_mask:0xf bank_mask:0xc
	v_mov_b32_dpp v55, v151 quad_perm:[0,1,2,3] row_mask:0xf bank_mask:0xc
	s_waitcnt vmcnt(26)
	v_pk_fma_f32 v[52:53], v[52:53], v[120:121], v[180:181]
	v_pk_fma_f32 v[54:55], v[54:55], v[122:123], v[182:183]
	v_pk_fma_f32 v[48:49], v[48:49], v[120:121], v[184:185]
	v_pk_fma_f32 v[50:51], v[50:51], v[122:123], v[186:187]
	s_add_u32 s98, s90, 0x10000
	s_addc_u32 s99, s91, 0
	global_store_dwordx4 v240, v[52:55], s[98:99] offset:512
	global_store_dwordx4 v242, v[48:51], s[98:99] offset:512
	v_mov_b32_dpp v148, v40 row_ror:8 row_mask:0xf bank_mask:0xf
	v_mov_b32_dpp v149, v41 row_ror:8 row_mask:0xf bank_mask:0xf
	v_mov_b32_dpp v150, v42 row_ror:8 row_mask:0xf bank_mask:0xf
	v_mov_b32_dpp v151, v43 row_ror:8 row_mask:0xf bank_mask:0xf
	v_mov_b32_dpp v40, v44 row_ror:8 row_mask:0xf bank_mask:0x3
	v_mov_b32_dpp v41, v45 row_ror:8 row_mask:0xf bank_mask:0x3
	v_mov_b32_dpp v42, v46 row_ror:8 row_mask:0xf bank_mask:0x3
	v_mov_b32_dpp v43, v47 row_ror:8 row_mask:0xf bank_mask:0x3
	v_mov_b32_dpp v44, v148 quad_perm:[0,1,2,3] row_mask:0xf bank_mask:0xc
	v_mov_b32_dpp v45, v149 quad_perm:[0,1,2,3] row_mask:0xf bank_mask:0xc
	v_mov_b32_dpp v46, v150 quad_perm:[0,1,2,3] row_mask:0xf bank_mask:0xc
	v_mov_b32_dpp v47, v151 quad_perm:[0,1,2,3] row_mask:0xf bank_mask:0xc
	s_waitcnt vmcnt(24)
;     __device__ __forceinline__ void operator()(const f32x4 (&acc)[2][2][4][2], const pg8::Unit& u, int wr, int wc, int fr, int fq) const {
;     ...
;         for (int bj = 0; bj < 2; ++bj) {
;             const int col = u.pn * 256 + bj * 128 + wc * 32 + 8 * fq;
;             const f32x4 g0 = *(const f32x4*)(gp + col) * coef, g1 = *(const f32x4*)(gp + col + 4) * coef;
; #pragma unroll
;             for (int ai = 0; ai < 2; ++ai)
; #pragma unroll
;                 for (int m = 0; m < 4; ++m) {
;                     const size_t off = (size_t)(row0 + ai * 128 + m * 16) * DM + col;
;                     const f32x4 x0 = *(const f32x4*)(base + off), x1 = *(const f32x4*)(base + off + 4);
;                     *(f32x4*)(out + off) = x0 + g0 * acc[ai][bj][m][0]; *(f32x4*)(out + off + 4) = x1 + g1 * acc[ai][bj][m][1];
;                     if (m & 1) asm volatile("" ::: "memory");
;                 }
	v_pk_fma_f32 v[44:45], v[44:45], v[120:121], v[188:189]
	v_pk_fma_f32 v[46:47], v[46:47], v[122:123], v[190:191]
	v_pk_fma_f32 v[40:41], v[40:41], v[120:121], v[192:193]
	v_pk_fma_f32 v[42:43], v[42:43], v[122:123], v[194:195]
	s_add_u32 s98, s90, 0x20000
	s_addc_u32 s99, s91, 0
	global_store_dwordx4 v240, v[44:47], s[98:99] offset:512
	global_store_dwordx4 v242, v[40:43], s[98:99] offset:512
	v_mov_b32_dpp v148, v32 row_ror:8 row_mask:0xf bank_mask:0xf
	v_mov_b32_dpp v149, v33 row_ror:8 row_mask:0xf bank_mask:0xf
	v_mov_b32_dpp v150, v34 row_ror:8 row_mask:0xf bank_mask:0xf
	v_mov_b32_dpp v151, v35 row_ror:8 row_mask:0xf bank_mask:0xf
	v_mov_b32_dpp v32, v36 row_ror:8 row_mask:0xf bank_mask:0x3
	v_mov_b32_dpp v33, v37 row_ror:8 row_mask:0xf bank_mask:0x3
	v_mov_b32_dpp v34, v38 row_ror:8 row_mask:0xf bank_mask:0x3
	v_mov_b32_dpp v35, v39 row_ror:8 row_mask:0xf bank_mask:0x3
	v_mov_b32_dpp v36, v148 quad_perm:[0,1,2,3] row_mask:0xf bank_mask:0xc
	v_mov_b32_dpp v37, v149 quad_perm:[0,1,2,3] row_mask:0xf bank_mask:0xc
	v_mov_b32_dpp v38, v150 quad_perm:[0,1,2,3] row_mask:0xf bank_mask:0xc
	v_mov_b32_dpp v39, v151 quad_perm:[0,1,2,3] row_mask:0xf bank_mask:0xc
	s_waitcnt vmcnt(22)
	v_pk_fma_f32 v[36:37], v[36:37], v[120:121], v[196:197]
	v_pk_fma_f32 v[38:39], v[38:39], v[122:123], v[198:199]
	v_pk_fma_f32 v[32:33], v[32:33], v[120:121], v[200:201]
	v_pk_fma_f32 v[34:35], v[34:35], v[122:123], v[202:203]
	s_add_u32 s98, s90, 0x30000
	s_addc_u32 s99, s91, 0
	global_store_dwordx4 v240, v[36:39], s[98:99] offset:512
	global_store_dwordx4 v242, v[32:35], s[98:99] offset:512
	v_mov_b32_dpp v148, v24 row_ror:8 row_mask:0xf bank_mask:0xf
	v_mov_b32_dpp v149, v25 row_ror:8 row_mask:0xf bank_mask:0xf
	v_mov_b32_dpp v150, v26 row_ror:8 row_mask:0xf bank_mask:0xf
	v_mov_b32_dpp v151, v27 row_ror:8 row_mask:0xf bank_mask:0xf
	v_mov_b32_dpp v24, v28 row_ror:8 row_mask:0xf bank_mask:0x3
	v_mov_b32_dpp v25, v29 row_ror:8 row_mask:0xf bank_mask:0x3
	v_mov_b32_dpp v26, v30 row_ror:8 row_mask:0xf bank_mask:0x3
	v_mov_b32_dpp v27, v31 row_ror:8 row_mask:0xf bank_mask:0x3
	v_mov_b32_dpp v28, v148 quad_perm:[0,1,2,3] row_mask:0xf bank_mask:0xc
	v_mov_b32_dpp v29, v149 quad_perm:[0,1,2,3] row_mask:0xf bank_mask:0xc
	v_mov_b32_dpp v30, v150 quad_perm:[0,1,2,3] row_mask:0xf bank_mask:0xc
	v_mov_b32_dpp v31, v151 quad_perm:[0,1,2,3] row_mask:0xf bank_mask:0xc
	s_waitcnt vmcnt(20)
	v_pk_fma_f32 v[28:29], v[28:29], v[120:121], v[208:209]
	v_pk_fma_f32 v[30:31], v[30:31], v[122:123], v[210:211]
	v_pk_fma_f32 v[24:25], v[24:25], v[120:121], v[212:213]
	v_pk_fma_f32 v[26:27], v[26:27], v[122:123], v[214:215]
	s_add_u32 s98, s90, 0x80000
	s_addc_u32 s99, s91, 0
	global_store_dwordx4 v240, v[28:31], s[98:99] offset:512
	global_store_dwordx4 v242, v[24:27], s[98:99] offset:512
	v_mov_b32_dpp v148, v16 row_ror:8 row_mask:0xf bank_mask:0xf
	v_mov_b32_dpp v149, v17 row_ror:8 row_mask:0xf bank_mask:0xf
	v_mov_b32_dpp v150, v18 row_ror:8 row_mask:0xf bank_mask:0xf
	v_mov_b32_dpp v151, v19 row_ror:8 row_mask:0xf bank_mask:0xf
	v_mov_b32_dpp v16, v20 row_ror:8 row_mask:0xf bank_mask:0x3
	v_mov_b32_dpp v17, v21 row_ror:8 row_mask:0xf bank_mask:0x3
	v_mov_b32_dpp v18, v22 row_ror:8 row_mask:0xf bank_mask:0x3
	v_mov_b32_dpp v19, v23 row_ror:8 row_mask:0xf bank_mask:0x3
	v_mov_b32_dpp v20, v148 quad_perm:[0,1,2,3] row_mask:0xf bank_mask:0xc
	v_mov_b32_dpp v21, v149 quad_perm:[0,1,2,3] row_mask:0xf bank_mask:0xc
	v_mov_b32_dpp v22, v150 quad_perm:[0,1,2,3] row_mask:0xf bank_mask:0xc
	v_mov_b32_dpp v23, v151 quad_perm:[0,1,2,3] row_mask:0xf bank_mask:0xc
	s_waitcnt vmcnt(18)
	v_pk_fma_f32 v[20:21], v[20:21], v[120:121], v[216:217]
	v_pk_fma_f32 v[22:23], v[22:23], v[122:123], v[218:219]
	v_pk_fma_f32 v[16:17], v[16:17], v[120:121], v[220:221]
	v_pk_fma_f32 v[18:19], v[18:19], v[122:123], v[222:223]
	s_add_u32 s98, s90, 0x90000
	s_addc_u32 s99, s91, 0
	global_store_dwordx4 v240, v[20:23], s[98:99] offset:512
	global_store_dwordx4 v242, v[16:19], s[98:99] offset:512
	v_mov_b32_dpp v148, v8 row_ror:8 row_mask:0xf bank_mask:0xf
	v_mov_b32_dpp v149, v9 row_ror:8 row_mask:0xf bank_mask:0xf
	v_mov_b32_dpp v150, v10 row_ror:8 row_mask:0xf bank_mask:0xf
	v_mov_b32_dpp v151, v11 row_ror:8 row_mask:0xf bank_mask:0xf
	v_mov_b32_dpp v8, v12 row_ror:8 row_mask:0xf bank_mask:0x3
	v_mov_b32_dpp v9, v13 row_ror:8 row_mask:0xf bank_mask:0x3
	v_mov_b32_dpp v10, v14 row_ror:8 row_mask:0xf bank_mask:0x3
	v_mov_b32_dpp v11, v15 row_ror:8 row_mask:0xf bank_mask:0x3
	v_mov_b32_dpp v12, v148 quad_perm:[0,1,2,3] row_mask:0xf bank_mask:0xc
	v_mov_b32_dpp v13, v149 quad_perm:[0,1,2,3] row_mask:0xf bank_mask:0xc
	v_mov_b32_dpp v14, v150 quad_perm:[0,1,2,3] row_mask:0xf bank_mask:0xc
	v_mov_b32_dpp v15, v151 quad_perm:[0,1,2,3] row_mask:0xf bank_mask:0xc
	s_waitcnt vmcnt(16)
	v_pk_fma_f32 v[12:13], v[12:13], v[120:121], v[224:225]
	v_pk_fma_f32 v[14:15], v[14:15], v[122:123], v[226:227]
	v_pk_fma_f32 v[8:9], v[8:9], v[120:121], v[228:229]
	v_pk_fma_f32 v[10:11], v[10:11], v[122:123], v[230:231]
	s_add_u32 s98, s90, 0xa0000
	s_addc_u32 s99, s91, 0
	global_store_dwordx4 v240, v[12:15], s[98:99] offset:512
	global_store_dwordx4 v242, v[8:11], s[98:99] offset:512
	v_mov_b32_dpp v148, v0 row_ror:8 row_mask:0xf bank_mask:0xf
	v_mov_b32_dpp v149, v1 row_ror:8 row_mask:0xf bank_mask:0xf
	v_mov_b32_dpp v150, v2 row_ror:8 row_mask:0xf bank_mask:0xf
	v_mov_b32_dpp v151, v3 row_ror:8 row_mask:0xf bank_mask:0xf
	v_mov_b32_dpp v0, v4 row_ror:8 row_mask:0xf bank_mask:0x3
	v_mov_b32_dpp v1, v5 row_ror:8 row_mask:0xf bank_mask:0x3
	v_mov_b32_dpp v2, v6 row_ror:8 row_mask:0xf bank_mask:0x3
	v_mov_b32_dpp v3, v7 row_ror:8 row_mask:0xf bank_mask:0x3
	v_mov_b32_dpp v4, v148 quad_perm:[0,1,2,3] row_mask:0xf bank_mask:0xc
	v_mov_b32_dpp v5, v149 quad_perm:[0,1,2,3] row_mask:0xf bank_mask:0xc
	v_mov_b32_dpp v6, v150 quad_perm:[0,1,2,3] row_mask:0xf bank_mask:0xc
	v_mov_b32_dpp v7, v151 quad_perm:[0,1,2,3] row_mask:0xf bank_mask:0xc
	s_waitcnt vmcnt(14)
	v_pk_fma_f32 v[4:5], v[4:5], v[120:121], v[232:233]
	v_pk_fma_f32 v[6:7], v[6:7], v[122:123], v[234:235]
	v_pk_fma_f32 v[0:1], v[0:1], v[120:121], v[236:237]
	v_pk_fma_f32 v[2:3], v[2:3], v[122:123], v[238:239]
	s_add_u32 s98, s90, 0xb0000
	s_addc_u32 s99, s91, 0
	global_store_dwordx4 v240, v[4:7], s[98:99] offset:512
	global_store_dwordx4 v242, v[0:3], s[98:99] offset:512
	s_and_b64 vcc, exec, s[0:1]
	s_mov_b64 s[0:1], -1
	s_cbranch_vccnz .LBB0_1381
	s_andn2_b64 vcc, exec, s[6:7]
	s_cbranch_vccnz .LBB0_1380
	s_barrier
	s_branch .LBB0_1380
